# phase-3 GEMM epilogue: bias loads hoisted + dwordx4 pairing (phases 10/14 edits kept; phase 16/8/12 batching dropped)
# baseline (speedup 1.0000x reference)
.LBB0_677:
	s_lshl_b32 s28, s26, 8
	s_ashr_i32 s29, s28, 31
	s_nop 15
	s_nop 15
	v_bfe_u32 v202, v206, 4, 1
	v_mul_u32_u24_e32 v202, 24, v202
	v_mov_b32_e32 v203, 0
	v_lshl_add_u64 v[164:165], s[28:29], 2, v[158:159]
	global_load_dwordx4 v[176:179], v[164:165], off
	global_load_dwordx4 v[180:183], v[164:165], off offset:64
	global_load_dwordx4 v[184:187], v[164:165], off offset:512
	global_load_dwordx4 v[188:191], v[164:165], off offset:576
	s_mul_i32 s0, s26, 0x84
	s_add_i32 s26, s0, s38
	s_ashr_i32 s27, s26, 31
	s_lshl_b64 s[26:27], s[26:27], 17
	s_add_u32 s26, s10, s26
	s_addc_u32 s27, s11, s27
	s_waitcnt vmcnt(0)
	v_mov_b64_e32 v[170:171], v[176:177]
	v_mov_b64_e32 v[172:173], v[178:179]
	v_pk_add_f32 v[126:127], v[126:127], v[170:171]
	s_nop 0
	v_mul_f32_e32 v169, 0x3d372713, v126
	v_mul_f32_e32 v169, v126, v169
	v_fma_f32 v169, v126, v169, v126
	v_mul_f32_e32 v169, 0x3f4c422a, v169
	v_add_f32_e32 v169, v169, v169
	v_mul_f32_e32 v169, 0x3fb8aa3b, v169
	v_exp_f32_e32 v169, v169
	v_pk_add_f32 v[128:129], v[128:129], v[172:173]
	v_mul_f32_e32 v126, 0.5, v126
	v_add_f32_e32 v169, 1.0, v169
	v_div_scale_f32 v170, s[28:29], v169, v169, 2.0
	v_rcp_f32_e32 v171, v170
	s_nop 0
	v_fma_f32 v172, -v170, v171, 1.0
	v_fmac_f32_e32 v171, v172, v171
	v_div_scale_f32 v172, vcc, 2.0, v169, 2.0
	v_mul_f32_e32 v173, v172, v171
	v_fma_f32 v174, -v170, v173, v172
	v_fmac_f32_e32 v173, v174, v171
	v_fma_f32 v170, -v170, v173, v172
	v_div_fmas_f32 v170, v170, v171, v173
	v_div_fixup_f32 v169, v170, v169, 2.0
	v_sub_f32_e32 v169, 1.0, v169
	v_add_f32_e32 v169, 1.0, v169
	v_mul_f32_e32 v126, v126, v169
	v_mul_f32_e32 v169, 0x3d372713, v127
	v_mul_f32_e32 v169, v127, v169
	v_fma_f32 v169, v127, v169, v127
	v_mul_f32_e32 v169, 0x3f4c422a, v169
	v_add_f32_e32 v169, v169, v169
	v_mul_f32_e32 v169, 0x3fb8aa3b, v169
	v_exp_f32_e32 v169, v169
	v_mul_f32_e32 v127, 0.5, v127
	v_add_f32_e32 v169, 1.0, v169
	v_div_scale_f32 v170, s[28:29], v169, v169, 2.0
	v_rcp_f32_e32 v171, v170
	s_nop 0
	v_fma_f32 v172, -v170, v171, 1.0
	v_fmac_f32_e32 v171, v172, v171
	v_div_scale_f32 v172, vcc, 2.0, v169, 2.0
	v_mul_f32_e32 v173, v172, v171
	v_fma_f32 v174, -v170, v173, v172
	v_fmac_f32_e32 v173, v174, v171
	v_fma_f32 v170, -v170, v173, v172
	v_div_fmas_f32 v170, v170, v171, v173
	v_div_fixup_f32 v169, v170, v169, 2.0
	v_sub_f32_e32 v169, 1.0, v169
	v_add_f32_e32 v169, 1.0, v169
	v_mul_f32_e32 v127, v127, v169
	v_mul_f32_e32 v169, 0x3d372713, v128
	v_mul_f32_e32 v169, v128, v169
	v_fma_f32 v169, v128, v169, v128
	v_mul_f32_e32 v169, 0x3f4c422a, v169
	v_add_f32_e32 v169, v169, v169
	v_mul_f32_e32 v169, 0x3fb8aa3b, v169
	v_exp_f32_e32 v169, v169
	v_mul_f32_e32 v128, 0.5, v128
	v_add_f32_e32 v169, 1.0, v169
	v_div_scale_f32 v170, s[28:29], v169, v169, 2.0
	v_rcp_f32_e32 v171, v170
	s_nop 0
	v_fma_f32 v172, -v170, v171, 1.0
	v_fmac_f32_e32 v171, v172, v171
	v_div_scale_f32 v172, vcc, 2.0, v169, 2.0
	v_mul_f32_e32 v173, v172, v171
	v_fma_f32 v174, -v170, v173, v172
	v_fmac_f32_e32 v173, v174, v171
	v_fma_f32 v170, -v170, v173, v172
	v_div_fmas_f32 v170, v170, v171, v173
	v_div_fixup_f32 v169, v170, v169, 2.0
	v_sub_f32_e32 v169, 1.0, v169
	v_add_f32_e32 v169, 1.0, v169
	v_mul_f32_e32 v169, v128, v169
	v_mul_f32_e32 v128, 0x3d372713, v129
	v_mul_f32_e32 v128, v129, v128
	v_fma_f32 v128, v129, v128, v129
	v_mul_f32_e32 v128, 0x3f4c422a, v128
	v_add_f32_e32 v128, v128, v128
	v_mul_f32_e32 v128, 0x3fb8aa3b, v128
	v_exp_f32_e32 v128, v128
	v_mul_f32_e32 v129, 0.5, v129
	v_add_f32_e32 v128, 1.0, v128
	v_div_scale_f32 v170, s[28:29], v128, v128, 2.0
	v_rcp_f32_e32 v171, v170
	s_nop 0
	v_fma_f32 v172, -v170, v171, 1.0
	v_fmac_f32_e32 v171, v172, v171
	v_div_scale_f32 v172, vcc, 2.0, v128, 2.0
	v_mul_f32_e32 v173, v172, v171
	v_fma_f32 v174, -v170, v173, v172
	v_fmac_f32_e32 v173, v174, v171
	v_fma_f32 v170, -v170, v173, v172
	v_div_fmas_f32 v170, v170, v171, v173
	v_div_fixup_f32 v128, v170, v128, 2.0
	v_sub_f32_e32 v128, 1.0, v128
	v_add_f32_e32 v128, 1.0, v128
	v_mul_f32_e32 v129, v129, v128
	v_cvt_pk_bf16_f32 v192, v126, v127
	v_lshl_add_u64 v[126:127], s[26:27], 0, v[142:143]
	v_lshl_add_u64 v[126:127], v[126:127], 0, v[140:141]
	v_cvt_pk_bf16_f32 v193, v169, v129
	s_nop 0
	v_mov_b64_e32 v[170:171], v[180:181]
	v_mov_b64_e32 v[172:173], v[182:183]
	s_nop 0
	v_pk_add_f32 v[122:123], v[122:123], v[170:171]
	s_nop 0
	v_mul_f32_e32 v128, 0x3d372713, v122
	v_mul_f32_e32 v128, v122, v128
	v_fma_f32 v128, v122, v128, v122
	v_mul_f32_e32 v128, 0x3f4c422a, v128
	v_add_f32_e32 v128, v128, v128
	v_mul_f32_e32 v128, 0x3fb8aa3b, v128
	v_exp_f32_e32 v128, v128
	v_pk_add_f32 v[124:125], v[124:125], v[172:173]
	v_mul_f32_e32 v122, 0.5, v122
	v_add_f32_e32 v128, 1.0, v128
	v_div_scale_f32 v129, s[28:29], v128, v128, 2.0
	v_rcp_f32_e32 v169, v129
	s_nop 0
	v_fma_f32 v170, -v129, v169, 1.0
	v_fmac_f32_e32 v169, v170, v169
	v_div_scale_f32 v170, vcc, 2.0, v128, 2.0
	v_mul_f32_e32 v171, v170, v169
	v_fma_f32 v172, -v129, v171, v170
	v_fmac_f32_e32 v171, v172, v169
	v_fma_f32 v129, -v129, v171, v170
	v_div_fmas_f32 v129, v129, v169, v171
	v_div_fixup_f32 v128, v129, v128, 2.0
	v_sub_f32_e32 v128, 1.0, v128
	v_add_f32_e32 v128, 1.0, v128
	v_mul_f32_e32 v122, v122, v128
	v_mul_f32_e32 v128, 0x3d372713, v123
	v_mul_f32_e32 v128, v123, v128
	v_fma_f32 v128, v123, v128, v123
	v_mul_f32_e32 v128, 0x3f4c422a, v128
	v_add_f32_e32 v128, v128, v128
	v_mul_f32_e32 v128, 0x3fb8aa3b, v128
	v_exp_f32_e32 v128, v128
	v_mul_f32_e32 v123, 0.5, v123
	v_add_f32_e32 v128, 1.0, v128
	v_div_scale_f32 v129, s[28:29], v128, v128, 2.0
	v_rcp_f32_e32 v169, v129
	s_nop 0
	v_fma_f32 v170, -v129, v169, 1.0
	v_fmac_f32_e32 v169, v170, v169
	v_div_scale_f32 v170, vcc, 2.0, v128, 2.0
	v_mul_f32_e32 v171, v170, v169
	v_fma_f32 v172, -v129, v171, v170
	v_fmac_f32_e32 v171, v172, v169
	v_fma_f32 v129, -v129, v171, v170
	v_div_fmas_f32 v129, v129, v169, v171
	v_div_fixup_f32 v128, v129, v128, 2.0
	v_sub_f32_e32 v128, 1.0, v128
	v_add_f32_e32 v128, 1.0, v128
	v_mul_f32_e32 v123, v123, v128
	v_mul_f32_e32 v128, 0x3d372713, v124
	v_mul_f32_e32 v128, v124, v128
	v_fma_f32 v128, v124, v128, v124
	v_mul_f32_e32 v128, 0x3f4c422a, v128
	v_add_f32_e32 v128, v128, v128
	v_mul_f32_e32 v128, 0x3fb8aa3b, v128
	v_exp_f32_e32 v128, v128
	v_mul_f32_e32 v124, 0.5, v124
	v_cvt_pk_bf16_f32 v194, v122, v123
	v_add_f32_e32 v128, 1.0, v128
	v_div_scale_f32 v129, s[28:29], v128, v128, 2.0
	v_rcp_f32_e32 v169, v129
	s_nop 0
	v_fma_f32 v170, -v129, v169, 1.0
	v_fmac_f32_e32 v169, v170, v169
	v_div_scale_f32 v170, vcc, 2.0, v128, 2.0
	v_mul_f32_e32 v171, v170, v169
	v_fma_f32 v172, -v129, v171, v170
	v_fmac_f32_e32 v171, v172, v169
	v_fma_f32 v129, -v129, v171, v170
	v_div_fmas_f32 v129, v129, v169, v171
	v_div_fixup_f32 v128, v129, v128, 2.0
	v_sub_f32_e32 v128, 1.0, v128
	v_add_f32_e32 v128, 1.0, v128
	v_mul_f32_e32 v124, v124, v128
	v_mul_f32_e32 v128, 0x3d372713, v125
	v_mul_f32_e32 v128, v125, v128
	v_fma_f32 v128, v125, v128, v125
	v_mul_f32_e32 v128, 0x3f4c422a, v128
	v_add_f32_e32 v128, v128, v128
	v_mul_f32_e32 v128, 0x3fb8aa3b, v128
	v_exp_f32_e32 v128, v128
	v_mul_f32_e32 v125, 0.5, v125
	v_add_f32_e32 v128, 1.0, v128
	v_div_scale_f32 v129, s[28:29], v128, v128, 2.0
	v_rcp_f32_e32 v169, v129
	s_nop 0
	v_fma_f32 v170, -v129, v169, 1.0
	v_fmac_f32_e32 v169, v170, v169
	v_div_scale_f32 v170, vcc, 2.0, v128, 2.0
	v_mul_f32_e32 v171, v170, v169
	v_fma_f32 v172, -v129, v171, v170
	v_fmac_f32_e32 v171, v172, v169
	v_fma_f32 v129, -v129, v171, v170
	v_div_fmas_f32 v129, v129, v169, v171
	v_div_fixup_f32 v128, v129, v128, 2.0
	v_sub_f32_e32 v128, 1.0, v128
	v_add_f32_e32 v128, 1.0, v128
	v_mul_f32_e32 v125, v125, v128
	v_cvt_pk_bf16_f32 v195, v124, v125
	s_nop 1
	v_permlane16_swap_b32_e32 v192, v194
	v_permlane16_swap_b32_e32 v193, v195
	v_lshl_add_u64 v[200:201], v[126:127], 0, v[202:203]
	global_store_dwordx4 v[200:201], v[192:195], off
	v_mov_b64_e32 v[122:123], v[184:185]
	v_mov_b64_e32 v[124:125], v[186:187]
	s_nop 0
	v_pk_add_f32 v[118:119], v[118:119], v[122:123]
	s_nop 0
	v_mul_f32_e32 v122, 0x3d372713, v118
	v_mul_f32_e32 v122, v118, v122
	v_fma_f32 v122, v118, v122, v118
	v_mul_f32_e32 v122, 0x3f4c422a, v122
	v_add_f32_e32 v122, v122, v122
	v_mul_f32_e32 v122, 0x3fb8aa3b, v122
	v_exp_f32_e32 v122, v122
	v_pk_add_f32 v[120:121], v[120:121], v[124:125]
	v_mul_f32_e32 v118, 0.5, v118
	v_add_f32_e32 v122, 1.0, v122
	v_div_scale_f32 v123, s[28:29], v122, v122, 2.0
	v_rcp_f32_e32 v124, v123
	s_nop 0
	v_fma_f32 v125, -v123, v124, 1.0
	v_fmac_f32_e32 v124, v125, v124
	v_div_scale_f32 v125, vcc, 2.0, v122, 2.0
	v_mul_f32_e32 v128, v125, v124
	v_fma_f32 v129, -v123, v128, v125
	v_fmac_f32_e32 v128, v129, v124
	v_fma_f32 v123, -v123, v128, v125
	v_div_fmas_f32 v123, v123, v124, v128
	v_div_fixup_f32 v122, v123, v122, 2.0
	v_sub_f32_e32 v122, 1.0, v122
	v_add_f32_e32 v122, 1.0, v122
	v_mul_f32_e32 v118, v118, v122
	v_mul_f32_e32 v122, 0x3d372713, v119
	v_mul_f32_e32 v122, v119, v122
	v_fma_f32 v122, v119, v122, v119
	v_mul_f32_e32 v122, 0x3f4c422a, v122
	v_add_f32_e32 v122, v122, v122
	v_mul_f32_e32 v122, 0x3fb8aa3b, v122
	v_exp_f32_e32 v122, v122
	v_mul_f32_e32 v119, 0.5, v119
	v_add_f32_e32 v122, 1.0, v122
	v_div_scale_f32 v123, s[28:29], v122, v122, 2.0
	v_rcp_f32_e32 v124, v123
	s_nop 0
	v_fma_f32 v125, -v123, v124, 1.0
	v_fmac_f32_e32 v124, v125, v124
	v_div_scale_f32 v125, vcc, 2.0, v122, 2.0
	v_mul_f32_e32 v128, v125, v124
	v_fma_f32 v129, -v123, v128, v125
	v_fmac_f32_e32 v128, v129, v124
	v_fma_f32 v123, -v123, v128, v125
	v_div_fmas_f32 v123, v123, v124, v128
	v_div_fixup_f32 v122, v123, v122, 2.0
	v_sub_f32_e32 v122, 1.0, v122
	v_add_f32_e32 v122, 1.0, v122
	v_mul_f32_e32 v119, v119, v122
	v_mul_f32_e32 v122, 0x3d372713, v120
	v_mul_f32_e32 v122, v120, v122
	v_fma_f32 v122, v120, v122, v120
	v_mul_f32_e32 v122, 0x3f4c422a, v122
	v_add_f32_e32 v122, v122, v122
	v_mul_f32_e32 v122, 0x3fb8aa3b, v122
	v_exp_f32_e32 v122, v122
	v_mul_f32_e32 v120, 0.5, v120
	v_cvt_pk_bf16_f32 v196, v118, v119
	v_add_f32_e32 v122, 1.0, v122
	v_div_scale_f32 v123, s[28:29], v122, v122, 2.0
	v_rcp_f32_e32 v124, v123
	s_nop 0
	v_fma_f32 v125, -v123, v124, 1.0
	v_fmac_f32_e32 v124, v125, v124
	v_div_scale_f32 v125, vcc, 2.0, v122, 2.0
	v_mul_f32_e32 v128, v125, v124
	v_fma_f32 v129, -v123, v128, v125
	v_fmac_f32_e32 v128, v129, v124
	v_fma_f32 v123, -v123, v128, v125
	v_div_fmas_f32 v123, v123, v124, v128
	v_div_fixup_f32 v122, v123, v122, 2.0
	v_sub_f32_e32 v122, 1.0, v122
	v_add_f32_e32 v122, 1.0, v122
	v_mul_f32_e32 v120, v120, v122
	v_mul_f32_e32 v122, 0x3d372713, v121
	v_mul_f32_e32 v122, v121, v122
	v_fma_f32 v122, v121, v122, v121
	v_mul_f32_e32 v122, 0x3f4c422a, v122
	v_add_f32_e32 v122, v122, v122
	v_mul_f32_e32 v122, 0x3fb8aa3b, v122
	v_exp_f32_e32 v122, v122
	v_mul_f32_e32 v121, 0.5, v121
	v_add_f32_e32 v122, 1.0, v122
	v_div_scale_f32 v123, s[28:29], v122, v122, 2.0
	v_rcp_f32_e32 v124, v123
	s_nop 0
	v_fma_f32 v125, -v123, v124, 1.0
	v_fmac_f32_e32 v124, v125, v124
	v_div_scale_f32 v125, vcc, 2.0, v122, 2.0
	v_mul_f32_e32 v128, v125, v124
	v_fma_f32 v129, -v123, v128, v125
	v_fmac_f32_e32 v128, v129, v124
	v_fma_f32 v123, -v123, v128, v125
	v_div_fmas_f32 v123, v123, v124, v128
	v_div_fixup_f32 v122, v123, v122, 2.0
	v_sub_f32_e32 v122, 1.0, v122
	v_add_f32_e32 v122, 1.0, v122
	v_mul_f32_e32 v121, v121, v122
	v_cvt_pk_bf16_f32 v197, v120, v121
	s_nop 0
	v_mov_b64_e32 v[118:119], v[188:189]
	v_mov_b64_e32 v[120:121], v[190:191]
	s_nop 0
	v_pk_add_f32 v[114:115], v[114:115], v[118:119]
	s_nop 0
	v_mul_f32_e32 v118, 0x3d372713, v114
	v_mul_f32_e32 v118, v114, v118
	v_fma_f32 v118, v114, v118, v114
	v_mul_f32_e32 v118, 0x3f4c422a, v118
	v_add_f32_e32 v118, v118, v118
	v_mul_f32_e32 v118, 0x3fb8aa3b, v118
	v_exp_f32_e32 v118, v118
	v_pk_add_f32 v[116:117], v[116:117], v[120:121]
	v_mul_f32_e32 v114, 0.5, v114
	v_add_f32_e32 v118, 1.0, v118
	v_div_scale_f32 v119, s[28:29], v118, v118, 2.0
	v_rcp_f32_e32 v120, v119
	s_nop 0
	v_fma_f32 v121, -v119, v120, 1.0
	v_fmac_f32_e32 v120, v121, v120
	v_div_scale_f32 v121, vcc, 2.0, v118, 2.0
	v_mul_f32_e32 v122, v121, v120
	v_fma_f32 v123, -v119, v122, v121
	v_fmac_f32_e32 v122, v123, v120
	v_fma_f32 v119, -v119, v122, v121
	v_div_fmas_f32 v119, v119, v120, v122
	v_div_fixup_f32 v118, v119, v118, 2.0
	v_sub_f32_e32 v118, 1.0, v118
	v_add_f32_e32 v118, 1.0, v118
	v_mul_f32_e32 v114, v114, v118
	v_mul_f32_e32 v118, 0x3d372713, v115
	v_mul_f32_e32 v118, v115, v118
	v_fma_f32 v118, v115, v118, v115
	v_mul_f32_e32 v118, 0x3f4c422a, v118
	v_add_f32_e32 v118, v118, v118
	v_mul_f32_e32 v118, 0x3fb8aa3b, v118
	v_exp_f32_e32 v118, v118
	v_mul_f32_e32 v115, 0.5, v115
	v_add_f32_e32 v118, 1.0, v118
	v_div_scale_f32 v119, s[28:29], v118, v118, 2.0
	v_rcp_f32_e32 v120, v119
	s_nop 0
	v_fma_f32 v121, -v119, v120, 1.0
	v_fmac_f32_e32 v120, v121, v120
	v_div_scale_f32 v121, vcc, 2.0, v118, 2.0
	v_mul_f32_e32 v122, v121, v120
	v_fma_f32 v123, -v119, v122, v121
	v_fmac_f32_e32 v122, v123, v120
	v_fma_f32 v119, -v119, v122, v121
	v_div_fmas_f32 v119, v119, v120, v122
	v_div_fixup_f32 v118, v119, v118, 2.0
	v_sub_f32_e32 v118, 1.0, v118
	v_add_f32_e32 v118, 1.0, v118
	v_mul_f32_e32 v115, v115, v118
	v_mul_f32_e32 v118, 0x3d372713, v116
	v_mul_f32_e32 v118, v116, v118
	v_fma_f32 v118, v116, v118, v116
	v_mul_f32_e32 v118, 0x3f4c422a, v118
	v_add_f32_e32 v118, v118, v118
	v_mul_f32_e32 v118, 0x3fb8aa3b, v118
	v_exp_f32_e32 v118, v118
	v_mul_f32_e32 v116, 0.5, v116
	v_cvt_pk_bf16_f32 v198, v114, v115
	v_add_f32_e32 v118, 1.0, v118
	v_div_scale_f32 v119, s[28:29], v118, v118, 2.0
	v_rcp_f32_e32 v120, v119
	s_nop 0
	v_fma_f32 v121, -v119, v120, 1.0
	v_fmac_f32_e32 v120, v121, v120
	v_div_scale_f32 v121, vcc, 2.0, v118, 2.0
	v_mul_f32_e32 v122, v121, v120
	v_fma_f32 v123, -v119, v122, v121
	v_fmac_f32_e32 v122, v123, v120
	v_fma_f32 v119, -v119, v122, v121
	v_div_fmas_f32 v119, v119, v120, v122
	v_div_fixup_f32 v118, v119, v118, 2.0
	v_sub_f32_e32 v118, 1.0, v118
	v_add_f32_e32 v118, 1.0, v118
	v_mul_f32_e32 v116, v116, v118
	v_mul_f32_e32 v118, 0x3d372713, v117
	v_mul_f32_e32 v118, v117, v118
	v_fma_f32 v118, v117, v118, v117
	v_mul_f32_e32 v118, 0x3f4c422a, v118
	v_add_f32_e32 v118, v118, v118
	v_mul_f32_e32 v118, 0x3fb8aa3b, v118
	v_exp_f32_e32 v118, v118
	v_mul_f32_e32 v117, 0.5, v117
	v_add_f32_e32 v118, 1.0, v118
	v_div_scale_f32 v119, s[28:29], v118, v118, 2.0
	v_rcp_f32_e32 v120, v119
	s_nop 0
	v_fma_f32 v121, -v119, v120, 1.0
	v_fmac_f32_e32 v120, v121, v120
	v_div_scale_f32 v121, vcc, 2.0, v118, 2.0
	v_mul_f32_e32 v122, v121, v120
	v_fma_f32 v123, -v119, v122, v121
	v_fmac_f32_e32 v122, v123, v120
	v_fma_f32 v119, -v119, v122, v121
	v_div_fmas_f32 v119, v119, v120, v122
	v_div_fixup_f32 v118, v119, v118, 2.0
	v_sub_f32_e32 v118, 1.0, v118
	v_add_f32_e32 v118, 1.0, v118
	v_mul_f32_e32 v117, v117, v118
	v_cvt_pk_bf16_f32 v199, v116, v117
	s_nop 1
	v_permlane16_swap_b32_e32 v196, v198
	v_permlane16_swap_b32_e32 v197, v199
	v_lshl_add_u64 v[200:201], v[126:127], 0, v[202:203]
	global_store_dwordx4 v[200:201], v[196:199], off offset:256
	v_mov_b64_e32 v[114:115], v[176:177]
	v_mov_b64_e32 v[116:117], v[178:179]
	s_nop 0
	v_pk_add_f32 v[110:111], v[110:111], v[114:115]
	s_nop 0
	v_mul_f32_e32 v114, 0x3d372713, v110
	v_mul_f32_e32 v114, v110, v114
	v_fma_f32 v114, v110, v114, v110
	v_mul_f32_e32 v114, 0x3f4c422a, v114
	v_add_f32_e32 v114, v114, v114
	v_mul_f32_e32 v114, 0x3fb8aa3b, v114
	v_exp_f32_e32 v114, v114
	v_pk_add_f32 v[112:113], v[112:113], v[116:117]
	v_mul_f32_e32 v110, 0.5, v110
	v_add_f32_e32 v114, 1.0, v114
	v_div_scale_f32 v115, s[28:29], v114, v114, 2.0
	v_rcp_f32_e32 v116, v115
	s_nop 0
	v_fma_f32 v117, -v115, v116, 1.0
	v_fmac_f32_e32 v116, v117, v116
	v_div_scale_f32 v117, vcc, 2.0, v114, 2.0
	v_mul_f32_e32 v118, v117, v116
	v_fma_f32 v119, -v115, v118, v117
	v_fmac_f32_e32 v118, v119, v116
	v_fma_f32 v115, -v115, v118, v117
	v_div_fmas_f32 v115, v115, v116, v118
	v_div_fixup_f32 v114, v115, v114, 2.0
	v_sub_f32_e32 v114, 1.0, v114
	v_add_f32_e32 v114, 1.0, v114
	v_mul_f32_e32 v110, v110, v114
	v_mul_f32_e32 v114, 0x3d372713, v111
	v_mul_f32_e32 v114, v111, v114
	v_fma_f32 v114, v111, v114, v111
	v_mul_f32_e32 v114, 0x3f4c422a, v114
	v_add_f32_e32 v114, v114, v114
	v_mul_f32_e32 v114, 0x3fb8aa3b, v114
	v_exp_f32_e32 v114, v114
	v_mul_f32_e32 v111, 0.5, v111
	v_add_f32_e32 v114, 1.0, v114
	v_div_scale_f32 v115, s[28:29], v114, v114, 2.0
	v_rcp_f32_e32 v116, v115
	s_nop 0
	v_fma_f32 v117, -v115, v116, 1.0
	v_fmac_f32_e32 v116, v117, v116
	v_div_scale_f32 v117, vcc, 2.0, v114, 2.0
	v_mul_f32_e32 v118, v117, v116
	v_fma_f32 v119, -v115, v118, v117
	v_fmac_f32_e32 v118, v119, v116
	v_fma_f32 v115, -v115, v118, v117
	v_div_fmas_f32 v115, v115, v116, v118
	v_div_fixup_f32 v114, v115, v114, 2.0
	v_sub_f32_e32 v114, 1.0, v114
	v_add_f32_e32 v114, 1.0, v114
	v_mul_f32_e32 v111, v111, v114
	v_mul_f32_e32 v114, 0x3d372713, v112
	v_mul_f32_e32 v114, v112, v114
	v_fma_f32 v114, v112, v114, v112
	v_mul_f32_e32 v114, 0x3f4c422a, v114
	v_add_f32_e32 v114, v114, v114
	v_mul_f32_e32 v114, 0x3fb8aa3b, v114
	v_exp_f32_e32 v114, v114
	v_mul_f32_e32 v112, 0.5, v112
	v_add_f32_e32 v114, 1.0, v114
	v_div_scale_f32 v115, s[28:29], v114, v114, 2.0
	v_rcp_f32_e32 v116, v115
	s_nop 0
	v_fma_f32 v117, -v115, v116, 1.0
	v_fmac_f32_e32 v116, v117, v116
	v_div_scale_f32 v117, vcc, 2.0, v114, 2.0
	v_mul_f32_e32 v118, v117, v116
	v_fma_f32 v119, -v115, v118, v117
	v_fmac_f32_e32 v118, v119, v116
	v_fma_f32 v115, -v115, v118, v117
	v_div_fmas_f32 v115, v115, v116, v118
	v_div_fixup_f32 v114, v115, v114, 2.0
	v_sub_f32_e32 v114, 1.0, v114
	v_add_f32_e32 v114, 1.0, v114
	v_mul_f32_e32 v114, v112, v114
	v_mul_f32_e32 v112, 0x3d372713, v113
	v_mul_f32_e32 v112, v113, v112
	v_fma_f32 v112, v113, v112, v113
	v_mul_f32_e32 v112, 0x3f4c422a, v112
	v_add_f32_e32 v112, v112, v112
	v_mul_f32_e32 v112, 0x3fb8aa3b, v112
	v_exp_f32_e32 v112, v112
	v_mul_f32_e32 v113, 0.5, v113
	v_add_f32_e32 v112, 1.0, v112
	v_div_scale_f32 v115, s[28:29], v112, v112, 2.0
	v_rcp_f32_e32 v116, v115
	s_nop 0
	v_fma_f32 v117, -v115, v116, 1.0
	v_fmac_f32_e32 v116, v117, v116
	v_div_scale_f32 v117, vcc, 2.0, v112, 2.0
	v_mul_f32_e32 v118, v117, v116
	v_fma_f32 v119, -v115, v118, v117
	v_fmac_f32_e32 v118, v119, v116
	v_fma_f32 v115, -v115, v118, v117
	v_div_fmas_f32 v115, v115, v116, v118
	v_div_fixup_f32 v112, v115, v112, 2.0
	v_sub_f32_e32 v112, 1.0, v112
	v_add_f32_e32 v112, 1.0, v112
	v_mul_f32_e32 v113, v113, v112
	v_cvt_pk_bf16_f32 v192, v110, v111
	v_lshl_add_u64 v[110:111], s[26:27], 0, v[144:145]
	v_lshl_add_u64 v[110:111], v[110:111], 0, v[140:141]
	v_cvt_pk_bf16_f32 v193, v114, v113
	s_nop 0
	v_mov_b64_e32 v[112:113], v[180:181]
	v_mov_b64_e32 v[114:115], v[182:183]
	s_nop 0
	v_pk_add_f32 v[106:107], v[106:107], v[112:113]
	s_nop 0
	v_mul_f32_e32 v112, 0x3d372713, v106
	v_mul_f32_e32 v112, v106, v112
	v_fma_f32 v112, v106, v112, v106
	v_mul_f32_e32 v112, 0x3f4c422a, v112
	v_add_f32_e32 v112, v112, v112
	v_mul_f32_e32 v112, 0x3fb8aa3b, v112
	v_exp_f32_e32 v112, v112
	v_pk_add_f32 v[108:109], v[108:109], v[114:115]
	v_mul_f32_e32 v106, 0.5, v106
	v_add_f32_e32 v112, 1.0, v112
	v_div_scale_f32 v113, s[28:29], v112, v112, 2.0
	v_rcp_f32_e32 v114, v113
	s_nop 0
	v_fma_f32 v115, -v113, v114, 1.0
	v_fmac_f32_e32 v114, v115, v114
	v_div_scale_f32 v115, vcc, 2.0, v112, 2.0
	v_mul_f32_e32 v116, v115, v114
	v_fma_f32 v117, -v113, v116, v115
	v_fmac_f32_e32 v116, v117, v114
	v_fma_f32 v113, -v113, v116, v115
	v_div_fmas_f32 v113, v113, v114, v116
	v_div_fixup_f32 v112, v113, v112, 2.0
	v_sub_f32_e32 v112, 1.0, v112
	v_add_f32_e32 v112, 1.0, v112
	v_mul_f32_e32 v106, v106, v112
	v_mul_f32_e32 v112, 0x3d372713, v107
	v_mul_f32_e32 v112, v107, v112
	v_fma_f32 v112, v107, v112, v107
	v_mul_f32_e32 v112, 0x3f4c422a, v112
	v_add_f32_e32 v112, v112, v112
	v_mul_f32_e32 v112, 0x3fb8aa3b, v112
	v_exp_f32_e32 v112, v112
	v_mul_f32_e32 v107, 0.5, v107
	v_add_f32_e32 v112, 1.0, v112
	v_div_scale_f32 v113, s[28:29], v112, v112, 2.0
	v_rcp_f32_e32 v114, v113
	s_nop 0
	v_fma_f32 v115, -v113, v114, 1.0
	v_fmac_f32_e32 v114, v115, v114
	v_div_scale_f32 v115, vcc, 2.0, v112, 2.0
	v_mul_f32_e32 v116, v115, v114
	v_fma_f32 v117, -v113, v116, v115
	v_fmac_f32_e32 v116, v117, v114
	v_fma_f32 v113, -v113, v116, v115
	v_div_fmas_f32 v113, v113, v114, v116
	v_div_fixup_f32 v112, v113, v112, 2.0
	v_sub_f32_e32 v112, 1.0, v112
	v_add_f32_e32 v112, 1.0, v112
	v_mul_f32_e32 v107, v107, v112
	v_mul_f32_e32 v112, 0x3d372713, v108
	v_mul_f32_e32 v112, v108, v112
	v_fma_f32 v112, v108, v112, v108
	v_mul_f32_e32 v112, 0x3f4c422a, v112
	v_add_f32_e32 v112, v112, v112
	v_mul_f32_e32 v112, 0x3fb8aa3b, v112
	v_exp_f32_e32 v112, v112
	v_mul_f32_e32 v108, 0.5, v108
	v_cvt_pk_bf16_f32 v194, v106, v107
	v_add_f32_e32 v112, 1.0, v112
	v_div_scale_f32 v113, s[28:29], v112, v112, 2.0
	v_rcp_f32_e32 v114, v113
	s_nop 0
	v_fma_f32 v115, -v113, v114, 1.0
	v_fmac_f32_e32 v114, v115, v114
	v_div_scale_f32 v115, vcc, 2.0, v112, 2.0
	v_mul_f32_e32 v116, v115, v114
	v_fma_f32 v117, -v113, v116, v115
	v_fmac_f32_e32 v116, v117, v114
	v_fma_f32 v113, -v113, v116, v115
	v_div_fmas_f32 v113, v113, v114, v116
	v_div_fixup_f32 v112, v113, v112, 2.0
	v_sub_f32_e32 v112, 1.0, v112
	v_add_f32_e32 v112, 1.0, v112
	v_mul_f32_e32 v108, v108, v112
	v_mul_f32_e32 v112, 0x3d372713, v109
	v_mul_f32_e32 v112, v109, v112
	v_fma_f32 v112, v109, v112, v109
	v_mul_f32_e32 v112, 0x3f4c422a, v112
	v_add_f32_e32 v112, v112, v112
	v_mul_f32_e32 v112, 0x3fb8aa3b, v112
	v_exp_f32_e32 v112, v112
	v_mul_f32_e32 v109, 0.5, v109
	v_add_f32_e32 v112, 1.0, v112
	v_div_scale_f32 v113, s[28:29], v112, v112, 2.0
	v_rcp_f32_e32 v114, v113
	s_nop 0
	v_fma_f32 v115, -v113, v114, 1.0
	v_fmac_f32_e32 v114, v115, v114
	v_div_scale_f32 v115, vcc, 2.0, v112, 2.0
	v_mul_f32_e32 v116, v115, v114
	v_fma_f32 v117, -v113, v116, v115
	v_fmac_f32_e32 v116, v117, v114
	v_fma_f32 v113, -v113, v116, v115
	v_div_fmas_f32 v113, v113, v114, v116
	v_div_fixup_f32 v112, v113, v112, 2.0
	v_sub_f32_e32 v112, 1.0, v112
	v_add_f32_e32 v112, 1.0, v112
	v_mul_f32_e32 v109, v109, v112
	v_cvt_pk_bf16_f32 v195, v108, v109
	s_nop 1
	v_permlane16_swap_b32_e32 v192, v194
	v_permlane16_swap_b32_e32 v193, v195
	v_lshl_add_u64 v[200:201], v[110:111], 0, v[202:203]
	global_store_dwordx4 v[200:201], v[192:195], off
	v_mov_b64_e32 v[106:107], v[184:185]
	v_mov_b64_e32 v[108:109], v[186:187]
	s_nop 0
	v_pk_add_f32 v[102:103], v[102:103], v[106:107]
	s_nop 0
	v_mul_f32_e32 v106, 0x3d372713, v102
	v_mul_f32_e32 v106, v102, v106
	v_fma_f32 v106, v102, v106, v102
	v_mul_f32_e32 v106, 0x3f4c422a, v106
	v_add_f32_e32 v106, v106, v106
	v_mul_f32_e32 v106, 0x3fb8aa3b, v106
	v_exp_f32_e32 v106, v106
	v_pk_add_f32 v[104:105], v[104:105], v[108:109]
	v_mul_f32_e32 v102, 0.5, v102
	v_add_f32_e32 v106, 1.0, v106
	v_div_scale_f32 v107, s[28:29], v106, v106, 2.0
	v_rcp_f32_e32 v108, v107
	s_nop 0
	v_fma_f32 v109, -v107, v108, 1.0
	v_fmac_f32_e32 v108, v109, v108
	v_div_scale_f32 v109, vcc, 2.0, v106, 2.0
	v_mul_f32_e32 v112, v109, v108
	v_fma_f32 v113, -v107, v112, v109
	v_fmac_f32_e32 v112, v113, v108
	v_fma_f32 v107, -v107, v112, v109
	v_div_fmas_f32 v107, v107, v108, v112
	v_div_fixup_f32 v106, v107, v106, 2.0
	v_sub_f32_e32 v106, 1.0, v106
	v_add_f32_e32 v106, 1.0, v106
	v_mul_f32_e32 v102, v102, v106
	v_mul_f32_e32 v106, 0x3d372713, v103
	v_mul_f32_e32 v106, v103, v106
	v_fma_f32 v106, v103, v106, v103
	v_mul_f32_e32 v106, 0x3f4c422a, v106
	v_add_f32_e32 v106, v106, v106
	v_mul_f32_e32 v106, 0x3fb8aa3b, v106
	v_exp_f32_e32 v106, v106
	v_mul_f32_e32 v103, 0.5, v103
	v_add_f32_e32 v106, 1.0, v106
	v_div_scale_f32 v107, s[28:29], v106, v106, 2.0
	v_rcp_f32_e32 v108, v107
	s_nop 0
	v_fma_f32 v109, -v107, v108, 1.0
	v_fmac_f32_e32 v108, v109, v108
	v_div_scale_f32 v109, vcc, 2.0, v106, 2.0
	v_mul_f32_e32 v112, v109, v108
	v_fma_f32 v113, -v107, v112, v109
	v_fmac_f32_e32 v112, v113, v108
	v_fma_f32 v107, -v107, v112, v109
	v_div_fmas_f32 v107, v107, v108, v112
	v_div_fixup_f32 v106, v107, v106, 2.0
	v_sub_f32_e32 v106, 1.0, v106
	v_add_f32_e32 v106, 1.0, v106
	v_mul_f32_e32 v103, v103, v106
	v_mul_f32_e32 v106, 0x3d372713, v104
	v_mul_f32_e32 v106, v104, v106
	v_fma_f32 v106, v104, v106, v104
	v_mul_f32_e32 v106, 0x3f4c422a, v106
	v_add_f32_e32 v106, v106, v106
	v_mul_f32_e32 v106, 0x3fb8aa3b, v106
	v_exp_f32_e32 v106, v106
	v_mul_f32_e32 v104, 0.5, v104
	v_cvt_pk_bf16_f32 v196, v102, v103
	v_add_f32_e32 v106, 1.0, v106
	v_div_scale_f32 v107, s[28:29], v106, v106, 2.0
	v_rcp_f32_e32 v108, v107
	s_nop 0
	v_fma_f32 v109, -v107, v108, 1.0
	v_fmac_f32_e32 v108, v109, v108
	v_div_scale_f32 v109, vcc, 2.0, v106, 2.0
	v_mul_f32_e32 v112, v109, v108
	v_fma_f32 v113, -v107, v112, v109
	v_fmac_f32_e32 v112, v113, v108
	v_fma_f32 v107, -v107, v112, v109
	v_div_fmas_f32 v107, v107, v108, v112
	v_div_fixup_f32 v106, v107, v106, 2.0
	v_sub_f32_e32 v106, 1.0, v106
	v_add_f32_e32 v106, 1.0, v106
	v_mul_f32_e32 v104, v104, v106
	v_mul_f32_e32 v106, 0x3d372713, v105
	v_mul_f32_e32 v106, v105, v106
	v_fma_f32 v106, v105, v106, v105
	v_mul_f32_e32 v106, 0x3f4c422a, v106
	v_add_f32_e32 v106, v106, v106
	v_mul_f32_e32 v106, 0x3fb8aa3b, v106
	v_exp_f32_e32 v106, v106
	v_mul_f32_e32 v105, 0.5, v105
	v_add_f32_e32 v106, 1.0, v106
	v_div_scale_f32 v107, s[28:29], v106, v106, 2.0
	v_rcp_f32_e32 v108, v107
	s_nop 0
	v_fma_f32 v109, -v107, v108, 1.0
	v_fmac_f32_e32 v108, v109, v108
	v_div_scale_f32 v109, vcc, 2.0, v106, 2.0
	v_mul_f32_e32 v112, v109, v108
	v_fma_f32 v113, -v107, v112, v109
	v_fmac_f32_e32 v112, v113, v108
	v_fma_f32 v107, -v107, v112, v109
	v_div_fmas_f32 v107, v107, v108, v112
	v_div_fixup_f32 v106, v107, v106, 2.0
	v_sub_f32_e32 v106, 1.0, v106
	v_add_f32_e32 v106, 1.0, v106
	v_mul_f32_e32 v105, v105, v106
	v_cvt_pk_bf16_f32 v197, v104, v105
	s_nop 0
	v_mov_b64_e32 v[102:103], v[188:189]
	v_mov_b64_e32 v[104:105], v[190:191]
	s_nop 0
	v_pk_add_f32 v[98:99], v[98:99], v[102:103]
	s_nop 0
	v_mul_f32_e32 v102, 0x3d372713, v98
	v_mul_f32_e32 v102, v98, v102
	v_fma_f32 v102, v98, v102, v98
	v_mul_f32_e32 v102, 0x3f4c422a, v102
	v_add_f32_e32 v102, v102, v102
	v_mul_f32_e32 v102, 0x3fb8aa3b, v102
	v_exp_f32_e32 v102, v102
	v_pk_add_f32 v[100:101], v[100:101], v[104:105]
	v_mul_f32_e32 v98, 0.5, v98
	v_add_f32_e32 v102, 1.0, v102
	v_div_scale_f32 v103, s[28:29], v102, v102, 2.0
	v_rcp_f32_e32 v104, v103
	s_nop 0
	v_fma_f32 v105, -v103, v104, 1.0
	v_fmac_f32_e32 v104, v105, v104
	v_div_scale_f32 v105, vcc, 2.0, v102, 2.0
	v_mul_f32_e32 v106, v105, v104
	v_fma_f32 v107, -v103, v106, v105
	v_fmac_f32_e32 v106, v107, v104
	v_fma_f32 v103, -v103, v106, v105
	v_div_fmas_f32 v103, v103, v104, v106
	v_div_fixup_f32 v102, v103, v102, 2.0
	v_sub_f32_e32 v102, 1.0, v102
	v_add_f32_e32 v102, 1.0, v102
	v_mul_f32_e32 v98, v98, v102
	v_mul_f32_e32 v102, 0x3d372713, v99
	v_mul_f32_e32 v102, v99, v102
	v_fma_f32 v102, v99, v102, v99
	v_mul_f32_e32 v102, 0x3f4c422a, v102
	v_add_f32_e32 v102, v102, v102
	v_mul_f32_e32 v102, 0x3fb8aa3b, v102
	v_exp_f32_e32 v102, v102
	v_mul_f32_e32 v99, 0.5, v99
	v_add_f32_e32 v102, 1.0, v102
	v_div_scale_f32 v103, s[28:29], v102, v102, 2.0
	v_rcp_f32_e32 v104, v103
	s_nop 0
	v_fma_f32 v105, -v103, v104, 1.0
	v_fmac_f32_e32 v104, v105, v104
	v_div_scale_f32 v105, vcc, 2.0, v102, 2.0
	v_mul_f32_e32 v106, v105, v104
	v_fma_f32 v107, -v103, v106, v105
	v_fmac_f32_e32 v106, v107, v104
	v_fma_f32 v103, -v103, v106, v105
	v_div_fmas_f32 v103, v103, v104, v106
	v_div_fixup_f32 v102, v103, v102, 2.0
	v_sub_f32_e32 v102, 1.0, v102
	v_add_f32_e32 v102, 1.0, v102
	v_mul_f32_e32 v99, v99, v102
	v_mul_f32_e32 v102, 0x3d372713, v100
	v_mul_f32_e32 v102, v100, v102
	v_fma_f32 v102, v100, v102, v100
	v_mul_f32_e32 v102, 0x3f4c422a, v102
	v_add_f32_e32 v102, v102, v102
	v_mul_f32_e32 v102, 0x3fb8aa3b, v102
	v_exp_f32_e32 v102, v102
	v_mul_f32_e32 v100, 0.5, v100
	v_cvt_pk_bf16_f32 v198, v98, v99
	v_add_f32_e32 v102, 1.0, v102
	v_div_scale_f32 v103, s[28:29], v102, v102, 2.0
	v_rcp_f32_e32 v104, v103
	s_nop 0
	v_fma_f32 v105, -v103, v104, 1.0
	v_fmac_f32_e32 v104, v105, v104
	v_div_scale_f32 v105, vcc, 2.0, v102, 2.0
	v_mul_f32_e32 v106, v105, v104
	v_fma_f32 v107, -v103, v106, v105
	v_fmac_f32_e32 v106, v107, v104
	v_fma_f32 v103, -v103, v106, v105
	v_div_fmas_f32 v103, v103, v104, v106
	v_div_fixup_f32 v102, v103, v102, 2.0
	v_sub_f32_e32 v102, 1.0, v102
	v_add_f32_e32 v102, 1.0, v102
	v_mul_f32_e32 v100, v100, v102
	v_mul_f32_e32 v102, 0x3d372713, v101
	v_mul_f32_e32 v102, v101, v102
	v_fma_f32 v102, v101, v102, v101
	v_mul_f32_e32 v102, 0x3f4c422a, v102
	v_add_f32_e32 v102, v102, v102
	v_mul_f32_e32 v102, 0x3fb8aa3b, v102
	v_exp_f32_e32 v102, v102
	v_mul_f32_e32 v101, 0.5, v101
	v_add_f32_e32 v102, 1.0, v102
	v_div_scale_f32 v103, s[28:29], v102, v102, 2.0
	v_rcp_f32_e32 v104, v103
	s_nop 0
	v_fma_f32 v105, -v103, v104, 1.0
	v_fmac_f32_e32 v104, v105, v104
	v_div_scale_f32 v105, vcc, 2.0, v102, 2.0
	v_mul_f32_e32 v106, v105, v104
	v_fma_f32 v107, -v103, v106, v105
	v_fmac_f32_e32 v106, v107, v104
	v_fma_f32 v103, -v103, v106, v105
	v_div_fmas_f32 v103, v103, v104, v106
	v_div_fixup_f32 v102, v103, v102, 2.0
	v_sub_f32_e32 v102, 1.0, v102
	v_add_f32_e32 v102, 1.0, v102
	v_mul_f32_e32 v101, v101, v102
	v_cvt_pk_bf16_f32 v199, v100, v101
	s_nop 1
	v_permlane16_swap_b32_e32 v196, v198
	v_permlane16_swap_b32_e32 v197, v199
	v_lshl_add_u64 v[200:201], v[110:111], 0, v[202:203]
	global_store_dwordx4 v[200:201], v[196:199], off offset:256
	v_mov_b64_e32 v[98:99], v[176:177]
	v_mov_b64_e32 v[100:101], v[178:179]
	s_nop 0
	v_pk_add_f32 v[94:95], v[94:95], v[98:99]
	s_nop 0
	v_mul_f32_e32 v98, 0x3d372713, v94
	v_mul_f32_e32 v98, v94, v98
	v_fma_f32 v98, v94, v98, v94
	v_mul_f32_e32 v98, 0x3f4c422a, v98
	v_add_f32_e32 v98, v98, v98
	v_mul_f32_e32 v98, 0x3fb8aa3b, v98
	v_exp_f32_e32 v98, v98
	v_pk_add_f32 v[96:97], v[96:97], v[100:101]
	v_mul_f32_e32 v94, 0.5, v94
	v_add_f32_e32 v98, 1.0, v98
	v_div_scale_f32 v99, s[28:29], v98, v98, 2.0
	v_rcp_f32_e32 v100, v99
	s_nop 0
	v_fma_f32 v101, -v99, v100, 1.0
	v_fmac_f32_e32 v100, v101, v100
	v_div_scale_f32 v101, vcc, 2.0, v98, 2.0
	v_mul_f32_e32 v102, v101, v100
	v_fma_f32 v103, -v99, v102, v101
	v_fmac_f32_e32 v102, v103, v100
	v_fma_f32 v99, -v99, v102, v101
	v_div_fmas_f32 v99, v99, v100, v102
	v_div_fixup_f32 v98, v99, v98, 2.0
	v_sub_f32_e32 v98, 1.0, v98
	v_add_f32_e32 v98, 1.0, v98
	v_mul_f32_e32 v94, v94, v98
	v_mul_f32_e32 v98, 0x3d372713, v95
	v_mul_f32_e32 v98, v95, v98
	v_fma_f32 v98, v95, v98, v95
	v_mul_f32_e32 v98, 0x3f4c422a, v98
	v_add_f32_e32 v98, v98, v98
	v_mul_f32_e32 v98, 0x3fb8aa3b, v98
	v_exp_f32_e32 v98, v98
	v_mul_f32_e32 v95, 0.5, v95
	v_add_f32_e32 v98, 1.0, v98
	v_div_scale_f32 v99, s[28:29], v98, v98, 2.0
	v_rcp_f32_e32 v100, v99
	s_nop 0
	v_fma_f32 v101, -v99, v100, 1.0
	v_fmac_f32_e32 v100, v101, v100
	v_div_scale_f32 v101, vcc, 2.0, v98, 2.0
	v_mul_f32_e32 v102, v101, v100
	v_fma_f32 v103, -v99, v102, v101
	v_fmac_f32_e32 v102, v103, v100
	v_fma_f32 v99, -v99, v102, v101
	v_div_fmas_f32 v99, v99, v100, v102
	v_div_fixup_f32 v98, v99, v98, 2.0
	v_sub_f32_e32 v98, 1.0, v98
	v_add_f32_e32 v98, 1.0, v98
	v_mul_f32_e32 v95, v95, v98
	v_mul_f32_e32 v98, 0x3d372713, v96
	v_mul_f32_e32 v98, v96, v98
	v_fma_f32 v98, v96, v98, v96
	v_mul_f32_e32 v98, 0x3f4c422a, v98
	v_add_f32_e32 v98, v98, v98
	v_mul_f32_e32 v98, 0x3fb8aa3b, v98
	v_exp_f32_e32 v98, v98
	v_mul_f32_e32 v96, 0.5, v96
	v_add_f32_e32 v98, 1.0, v98
	v_div_scale_f32 v99, s[28:29], v98, v98, 2.0
	v_rcp_f32_e32 v100, v99
	s_nop 0
	v_fma_f32 v101, -v99, v100, 1.0
	v_fmac_f32_e32 v100, v101, v100
	v_div_scale_f32 v101, vcc, 2.0, v98, 2.0
	v_mul_f32_e32 v102, v101, v100
	v_fma_f32 v103, -v99, v102, v101
	v_fmac_f32_e32 v102, v103, v100
	v_fma_f32 v99, -v99, v102, v101
	v_div_fmas_f32 v99, v99, v100, v102
	v_div_fixup_f32 v98, v99, v98, 2.0
	v_sub_f32_e32 v98, 1.0, v98
	v_add_f32_e32 v98, 1.0, v98
	v_mul_f32_e32 v98, v96, v98
	v_mul_f32_e32 v96, 0x3d372713, v97
	v_mul_f32_e32 v96, v97, v96
	v_fma_f32 v96, v97, v96, v97
	v_mul_f32_e32 v96, 0x3f4c422a, v96
	v_add_f32_e32 v96, v96, v96
	v_mul_f32_e32 v96, 0x3fb8aa3b, v96
	v_exp_f32_e32 v96, v96
	v_mul_f32_e32 v97, 0.5, v97
	v_add_f32_e32 v96, 1.0, v96
	v_div_scale_f32 v99, s[28:29], v96, v96, 2.0
	v_rcp_f32_e32 v100, v99
	s_nop 0
	v_fma_f32 v101, -v99, v100, 1.0
	v_fmac_f32_e32 v100, v101, v100
	v_div_scale_f32 v101, vcc, 2.0, v96, 2.0
	v_mul_f32_e32 v102, v101, v100
	v_fma_f32 v103, -v99, v102, v101
	v_fmac_f32_e32 v102, v103, v100
	v_fma_f32 v99, -v99, v102, v101
	v_div_fmas_f32 v99, v99, v100, v102
	v_div_fixup_f32 v96, v99, v96, 2.0
	v_sub_f32_e32 v96, 1.0, v96
	v_add_f32_e32 v96, 1.0, v96
	v_mul_f32_e32 v97, v97, v96
	v_cvt_pk_bf16_f32 v192, v94, v95
	v_lshl_add_u64 v[94:95], s[26:27], 0, v[146:147]
	v_lshl_add_u64 v[94:95], v[94:95], 0, v[140:141]
	v_cvt_pk_bf16_f32 v193, v98, v97
	s_nop 0
	v_mov_b64_e32 v[96:97], v[180:181]
	v_mov_b64_e32 v[98:99], v[182:183]
	s_nop 0
	v_pk_add_f32 v[90:91], v[90:91], v[96:97]
	s_nop 0
	v_mul_f32_e32 v96, 0x3d372713, v90
	v_mul_f32_e32 v96, v90, v96
	v_fma_f32 v96, v90, v96, v90
	v_mul_f32_e32 v96, 0x3f4c422a, v96
	v_add_f32_e32 v96, v96, v96
	v_mul_f32_e32 v96, 0x3fb8aa3b, v96
	v_exp_f32_e32 v96, v96
	v_pk_add_f32 v[92:93], v[92:93], v[98:99]
	v_mul_f32_e32 v90, 0.5, v90
	v_add_f32_e32 v96, 1.0, v96
	v_div_scale_f32 v97, s[28:29], v96, v96, 2.0
	v_rcp_f32_e32 v98, v97
	s_nop 0
	v_fma_f32 v99, -v97, v98, 1.0
	v_fmac_f32_e32 v98, v99, v98
	v_div_scale_f32 v99, vcc, 2.0, v96, 2.0
	v_mul_f32_e32 v100, v99, v98
	v_fma_f32 v101, -v97, v100, v99
	v_fmac_f32_e32 v100, v101, v98
	v_fma_f32 v97, -v97, v100, v99
	v_div_fmas_f32 v97, v97, v98, v100
	v_div_fixup_f32 v96, v97, v96, 2.0
	v_sub_f32_e32 v96, 1.0, v96
	v_add_f32_e32 v96, 1.0, v96
	v_mul_f32_e32 v90, v90, v96
	v_mul_f32_e32 v96, 0x3d372713, v91
	v_mul_f32_e32 v96, v91, v96
	v_fma_f32 v96, v91, v96, v91
	v_mul_f32_e32 v96, 0x3f4c422a, v96
	v_add_f32_e32 v96, v96, v96
	v_mul_f32_e32 v96, 0x3fb8aa3b, v96
	v_exp_f32_e32 v96, v96
	v_mul_f32_e32 v91, 0.5, v91
	v_add_f32_e32 v96, 1.0, v96
	v_div_scale_f32 v97, s[28:29], v96, v96, 2.0
	v_rcp_f32_e32 v98, v97
	s_nop 0
	v_fma_f32 v99, -v97, v98, 1.0
	v_fmac_f32_e32 v98, v99, v98
	v_div_scale_f32 v99, vcc, 2.0, v96, 2.0
	v_mul_f32_e32 v100, v99, v98
	v_fma_f32 v101, -v97, v100, v99
	v_fmac_f32_e32 v100, v101, v98
	v_fma_f32 v97, -v97, v100, v99
	v_div_fmas_f32 v97, v97, v98, v100
	v_div_fixup_f32 v96, v97, v96, 2.0
	v_sub_f32_e32 v96, 1.0, v96
	v_add_f32_e32 v96, 1.0, v96
	v_mul_f32_e32 v91, v91, v96
	v_mul_f32_e32 v96, 0x3d372713, v92
	v_mul_f32_e32 v96, v92, v96
	v_fma_f32 v96, v92, v96, v92
	v_mul_f32_e32 v96, 0x3f4c422a, v96
	v_add_f32_e32 v96, v96, v96
	v_mul_f32_e32 v96, 0x3fb8aa3b, v96
	v_exp_f32_e32 v96, v96
	v_mul_f32_e32 v92, 0.5, v92
	v_cvt_pk_bf16_f32 v194, v90, v91
	v_add_f32_e32 v96, 1.0, v96
	v_div_scale_f32 v97, s[28:29], v96, v96, 2.0
	v_rcp_f32_e32 v98, v97
	s_nop 0
	v_fma_f32 v99, -v97, v98, 1.0
	v_fmac_f32_e32 v98, v99, v98
	v_div_scale_f32 v99, vcc, 2.0, v96, 2.0
	v_mul_f32_e32 v100, v99, v98
	v_fma_f32 v101, -v97, v100, v99
	v_fmac_f32_e32 v100, v101, v98
	v_fma_f32 v97, -v97, v100, v99
	v_div_fmas_f32 v97, v97, v98, v100
	v_div_fixup_f32 v96, v97, v96, 2.0
	v_sub_f32_e32 v96, 1.0, v96
	v_add_f32_e32 v96, 1.0, v96
	v_mul_f32_e32 v92, v92, v96
	v_mul_f32_e32 v96, 0x3d372713, v93
	v_mul_f32_e32 v96, v93, v96
	v_fma_f32 v96, v93, v96, v93
	v_mul_f32_e32 v96, 0x3f4c422a, v96
	v_add_f32_e32 v96, v96, v96
	v_mul_f32_e32 v96, 0x3fb8aa3b, v96
	v_exp_f32_e32 v96, v96
	v_mul_f32_e32 v93, 0.5, v93
	v_add_f32_e32 v96, 1.0, v96
	v_div_scale_f32 v97, s[28:29], v96, v96, 2.0
	v_rcp_f32_e32 v98, v97
	s_nop 0
	v_fma_f32 v99, -v97, v98, 1.0
	v_fmac_f32_e32 v98, v99, v98
	v_div_scale_f32 v99, vcc, 2.0, v96, 2.0
	v_mul_f32_e32 v100, v99, v98
	v_fma_f32 v101, -v97, v100, v99
	v_fmac_f32_e32 v100, v101, v98
	v_fma_f32 v97, -v97, v100, v99
	v_div_fmas_f32 v97, v97, v98, v100
	v_div_fixup_f32 v96, v97, v96, 2.0
	v_sub_f32_e32 v96, 1.0, v96
	v_add_f32_e32 v96, 1.0, v96
	v_mul_f32_e32 v93, v93, v96
	v_cvt_pk_bf16_f32 v195, v92, v93
	s_nop 1
	v_permlane16_swap_b32_e32 v192, v194
	v_permlane16_swap_b32_e32 v193, v195
	v_lshl_add_u64 v[200:201], v[94:95], 0, v[202:203]
	global_store_dwordx4 v[200:201], v[192:195], off
	v_mov_b64_e32 v[90:91], v[184:185]
	v_mov_b64_e32 v[92:93], v[186:187]
	s_nop 0
	v_pk_add_f32 v[86:87], v[86:87], v[90:91]
	s_nop 0
	v_mul_f32_e32 v90, 0x3d372713, v86
	v_mul_f32_e32 v90, v86, v90
	v_fma_f32 v90, v86, v90, v86
	v_mul_f32_e32 v90, 0x3f4c422a, v90
	v_add_f32_e32 v90, v90, v90
	v_mul_f32_e32 v90, 0x3fb8aa3b, v90
	v_exp_f32_e32 v90, v90
	v_pk_add_f32 v[88:89], v[88:89], v[92:93]
	v_mul_f32_e32 v86, 0.5, v86
	v_add_f32_e32 v90, 1.0, v90
	v_div_scale_f32 v91, s[28:29], v90, v90, 2.0
	v_rcp_f32_e32 v92, v91
	s_nop 0
	v_fma_f32 v93, -v91, v92, 1.0
	v_fmac_f32_e32 v92, v93, v92
	v_div_scale_f32 v93, vcc, 2.0, v90, 2.0
	v_mul_f32_e32 v96, v93, v92
	v_fma_f32 v97, -v91, v96, v93
	v_fmac_f32_e32 v96, v97, v92
	v_fma_f32 v91, -v91, v96, v93
	v_div_fmas_f32 v91, v91, v92, v96
	v_div_fixup_f32 v90, v91, v90, 2.0
	v_sub_f32_e32 v90, 1.0, v90
	v_add_f32_e32 v90, 1.0, v90
	v_mul_f32_e32 v86, v86, v90
	v_mul_f32_e32 v90, 0x3d372713, v87
	v_mul_f32_e32 v90, v87, v90
	v_fma_f32 v90, v87, v90, v87
	v_mul_f32_e32 v90, 0x3f4c422a, v90
	v_add_f32_e32 v90, v90, v90
	v_mul_f32_e32 v90, 0x3fb8aa3b, v90
	v_exp_f32_e32 v90, v90
	v_mul_f32_e32 v87, 0.5, v87
	v_add_f32_e32 v90, 1.0, v90
	v_div_scale_f32 v91, s[28:29], v90, v90, 2.0
	v_rcp_f32_e32 v92, v91
	s_nop 0
	v_fma_f32 v93, -v91, v92, 1.0
	v_fmac_f32_e32 v92, v93, v92
	v_div_scale_f32 v93, vcc, 2.0, v90, 2.0
	v_mul_f32_e32 v96, v93, v92
	v_fma_f32 v97, -v91, v96, v93
	v_fmac_f32_e32 v96, v97, v92
	v_fma_f32 v91, -v91, v96, v93
	v_div_fmas_f32 v91, v91, v92, v96
	v_div_fixup_f32 v90, v91, v90, 2.0
	v_sub_f32_e32 v90, 1.0, v90
	v_add_f32_e32 v90, 1.0, v90
	v_mul_f32_e32 v87, v87, v90
	v_mul_f32_e32 v90, 0x3d372713, v88
	v_mul_f32_e32 v90, v88, v90
	v_fma_f32 v90, v88, v90, v88
	v_mul_f32_e32 v90, 0x3f4c422a, v90
	v_add_f32_e32 v90, v90, v90
	v_mul_f32_e32 v90, 0x3fb8aa3b, v90
	v_exp_f32_e32 v90, v90
	v_mul_f32_e32 v88, 0.5, v88
	v_cvt_pk_bf16_f32 v196, v86, v87
	v_add_f32_e32 v90, 1.0, v90
	v_div_scale_f32 v91, s[28:29], v90, v90, 2.0
	v_rcp_f32_e32 v92, v91
	s_nop 0
	v_fma_f32 v93, -v91, v92, 1.0
	v_fmac_f32_e32 v92, v93, v92
	v_div_scale_f32 v93, vcc, 2.0, v90, 2.0
	v_mul_f32_e32 v96, v93, v92
	v_fma_f32 v97, -v91, v96, v93
	v_fmac_f32_e32 v96, v97, v92
	v_fma_f32 v91, -v91, v96, v93
	v_div_fmas_f32 v91, v91, v92, v96
	v_div_fixup_f32 v90, v91, v90, 2.0
	v_sub_f32_e32 v90, 1.0, v90
	v_add_f32_e32 v90, 1.0, v90
	v_mul_f32_e32 v88, v88, v90
	v_mul_f32_e32 v90, 0x3d372713, v89
	v_mul_f32_e32 v90, v89, v90
	v_fma_f32 v90, v89, v90, v89
	v_mul_f32_e32 v90, 0x3f4c422a, v90
	v_add_f32_e32 v90, v90, v90
	v_mul_f32_e32 v90, 0x3fb8aa3b, v90
	v_exp_f32_e32 v90, v90
	v_mul_f32_e32 v89, 0.5, v89
	v_add_f32_e32 v90, 1.0, v90
	v_div_scale_f32 v91, s[28:29], v90, v90, 2.0
	v_rcp_f32_e32 v92, v91
	s_nop 0
	v_fma_f32 v93, -v91, v92, 1.0
	v_fmac_f32_e32 v92, v93, v92
	v_div_scale_f32 v93, vcc, 2.0, v90, 2.0
	v_mul_f32_e32 v96, v93, v92
	v_fma_f32 v97, -v91, v96, v93
	v_fmac_f32_e32 v96, v97, v92
	v_fma_f32 v91, -v91, v96, v93
	v_div_fmas_f32 v91, v91, v92, v96
	v_div_fixup_f32 v90, v91, v90, 2.0
	v_sub_f32_e32 v90, 1.0, v90
	v_add_f32_e32 v90, 1.0, v90
	v_mul_f32_e32 v89, v89, v90
	v_cvt_pk_bf16_f32 v197, v88, v89
	s_nop 0
	v_mov_b64_e32 v[86:87], v[188:189]
	v_mov_b64_e32 v[88:89], v[190:191]
	s_nop 0
	v_pk_add_f32 v[82:83], v[82:83], v[86:87]
	s_nop 0
	v_mul_f32_e32 v86, 0x3d372713, v82
	v_mul_f32_e32 v86, v82, v86
	v_fma_f32 v86, v82, v86, v82
	v_mul_f32_e32 v86, 0x3f4c422a, v86
	v_add_f32_e32 v86, v86, v86
	v_mul_f32_e32 v86, 0x3fb8aa3b, v86
	v_exp_f32_e32 v86, v86
	v_pk_add_f32 v[84:85], v[84:85], v[88:89]
	v_mul_f32_e32 v82, 0.5, v82
	v_add_f32_e32 v86, 1.0, v86
	v_div_scale_f32 v87, s[28:29], v86, v86, 2.0
	v_rcp_f32_e32 v88, v87
	s_nop 0
	v_fma_f32 v89, -v87, v88, 1.0
	v_fmac_f32_e32 v88, v89, v88
	v_div_scale_f32 v89, vcc, 2.0, v86, 2.0
	v_mul_f32_e32 v90, v89, v88
	v_fma_f32 v91, -v87, v90, v89
	v_fmac_f32_e32 v90, v91, v88
	v_fma_f32 v87, -v87, v90, v89
	v_div_fmas_f32 v87, v87, v88, v90
	v_div_fixup_f32 v86, v87, v86, 2.0
	v_sub_f32_e32 v86, 1.0, v86
	v_add_f32_e32 v86, 1.0, v86
	v_mul_f32_e32 v82, v82, v86
	v_mul_f32_e32 v86, 0x3d372713, v83
	v_mul_f32_e32 v86, v83, v86
	v_fma_f32 v86, v83, v86, v83
	v_mul_f32_e32 v86, 0x3f4c422a, v86
	v_add_f32_e32 v86, v86, v86
	v_mul_f32_e32 v86, 0x3fb8aa3b, v86
	v_exp_f32_e32 v86, v86
	v_mul_f32_e32 v83, 0.5, v83
	v_add_f32_e32 v86, 1.0, v86
	v_div_scale_f32 v87, s[28:29], v86, v86, 2.0
	v_rcp_f32_e32 v88, v87
	s_nop 0
	v_fma_f32 v89, -v87, v88, 1.0
	v_fmac_f32_e32 v88, v89, v88
	v_div_scale_f32 v89, vcc, 2.0, v86, 2.0
	v_mul_f32_e32 v90, v89, v88
	v_fma_f32 v91, -v87, v90, v89
	v_fmac_f32_e32 v90, v91, v88
	v_fma_f32 v87, -v87, v90, v89
	v_div_fmas_f32 v87, v87, v88, v90
	v_div_fixup_f32 v86, v87, v86, 2.0
	v_sub_f32_e32 v86, 1.0, v86
	v_add_f32_e32 v86, 1.0, v86
	v_mul_f32_e32 v83, v83, v86
	v_mul_f32_e32 v86, 0x3d372713, v84
	v_mul_f32_e32 v86, v84, v86
	v_fma_f32 v86, v84, v86, v84
	v_mul_f32_e32 v86, 0x3f4c422a, v86
	v_add_f32_e32 v86, v86, v86
	v_mul_f32_e32 v86, 0x3fb8aa3b, v86
	v_exp_f32_e32 v86, v86
	v_mul_f32_e32 v84, 0.5, v84
	v_cvt_pk_bf16_f32 v198, v82, v83
	v_add_f32_e32 v86, 1.0, v86
	v_div_scale_f32 v87, s[28:29], v86, v86, 2.0
	v_rcp_f32_e32 v88, v87
	s_nop 0
	v_fma_f32 v89, -v87, v88, 1.0
	v_fmac_f32_e32 v88, v89, v88
	v_div_scale_f32 v89, vcc, 2.0, v86, 2.0
	v_mul_f32_e32 v90, v89, v88
	v_fma_f32 v91, -v87, v90, v89
	v_fmac_f32_e32 v90, v91, v88
	v_fma_f32 v87, -v87, v90, v89
	v_div_fmas_f32 v87, v87, v88, v90
	v_div_fixup_f32 v86, v87, v86, 2.0
	v_sub_f32_e32 v86, 1.0, v86
	v_add_f32_e32 v86, 1.0, v86
	v_mul_f32_e32 v84, v84, v86
	v_mul_f32_e32 v86, 0x3d372713, v85
	v_mul_f32_e32 v86, v85, v86
	v_fma_f32 v86, v85, v86, v85
	v_mul_f32_e32 v86, 0x3f4c422a, v86
	v_add_f32_e32 v86, v86, v86
	v_mul_f32_e32 v86, 0x3fb8aa3b, v86
	v_exp_f32_e32 v86, v86
	v_mul_f32_e32 v85, 0.5, v85
	v_add_f32_e32 v86, 1.0, v86
	v_div_scale_f32 v87, s[28:29], v86, v86, 2.0
	v_rcp_f32_e32 v88, v87
	s_nop 0
	v_fma_f32 v89, -v87, v88, 1.0
	v_fmac_f32_e32 v88, v89, v88
	v_div_scale_f32 v89, vcc, 2.0, v86, 2.0
	v_mul_f32_e32 v90, v89, v88
	v_fma_f32 v91, -v87, v90, v89
	v_fmac_f32_e32 v90, v91, v88
	v_fma_f32 v87, -v87, v90, v89
	v_div_fmas_f32 v87, v87, v88, v90
	v_div_fixup_f32 v86, v87, v86, 2.0
	v_sub_f32_e32 v86, 1.0, v86
	v_add_f32_e32 v86, 1.0, v86
	v_mul_f32_e32 v85, v85, v86
	v_cvt_pk_bf16_f32 v199, v84, v85
	s_nop 1
	v_permlane16_swap_b32_e32 v196, v198
	v_permlane16_swap_b32_e32 v197, v199
	v_lshl_add_u64 v[200:201], v[94:95], 0, v[202:203]
	global_store_dwordx4 v[200:201], v[196:199], off offset:256
	v_mov_b64_e32 v[82:83], v[176:177]
	v_mov_b64_e32 v[84:85], v[178:179]
	s_nop 0
	v_pk_add_f32 v[78:79], v[78:79], v[82:83]
	s_nop 0
	v_mul_f32_e32 v82, 0x3d372713, v78
	v_mul_f32_e32 v82, v78, v82
	v_fma_f32 v82, v78, v82, v78
	v_mul_f32_e32 v82, 0x3f4c422a, v82
	v_add_f32_e32 v82, v82, v82
	v_mul_f32_e32 v82, 0x3fb8aa3b, v82
	v_exp_f32_e32 v82, v82
	v_pk_add_f32 v[80:81], v[80:81], v[84:85]
	v_mul_f32_e32 v78, 0.5, v78
	v_add_f32_e32 v82, 1.0, v82
	v_div_scale_f32 v83, s[28:29], v82, v82, 2.0
	v_rcp_f32_e32 v84, v83
	s_nop 0
	v_fma_f32 v85, -v83, v84, 1.0
	v_fmac_f32_e32 v84, v85, v84
	v_div_scale_f32 v85, vcc, 2.0, v82, 2.0
	v_mul_f32_e32 v86, v85, v84
	v_fma_f32 v87, -v83, v86, v85
	v_fmac_f32_e32 v86, v87, v84
	v_fma_f32 v83, -v83, v86, v85
	v_div_fmas_f32 v83, v83, v84, v86
	v_div_fixup_f32 v82, v83, v82, 2.0
	v_sub_f32_e32 v82, 1.0, v82
	v_add_f32_e32 v82, 1.0, v82
	v_mul_f32_e32 v78, v78, v82
	v_mul_f32_e32 v82, 0x3d372713, v79
	v_mul_f32_e32 v82, v79, v82
	v_fma_f32 v82, v79, v82, v79
	v_mul_f32_e32 v82, 0x3f4c422a, v82
	v_add_f32_e32 v82, v82, v82
	v_mul_f32_e32 v82, 0x3fb8aa3b, v82
	v_exp_f32_e32 v82, v82
	v_mul_f32_e32 v79, 0.5, v79
	v_add_f32_e32 v82, 1.0, v82
	v_div_scale_f32 v83, s[28:29], v82, v82, 2.0
	v_rcp_f32_e32 v84, v83
	s_nop 0
	v_fma_f32 v85, -v83, v84, 1.0
	v_fmac_f32_e32 v84, v85, v84
	v_div_scale_f32 v85, vcc, 2.0, v82, 2.0
	v_mul_f32_e32 v86, v85, v84
	v_fma_f32 v87, -v83, v86, v85
	v_fmac_f32_e32 v86, v87, v84
	v_fma_f32 v83, -v83, v86, v85
	v_div_fmas_f32 v83, v83, v84, v86
	v_div_fixup_f32 v82, v83, v82, 2.0
	v_sub_f32_e32 v82, 1.0, v82
	v_add_f32_e32 v82, 1.0, v82
	v_mul_f32_e32 v79, v79, v82
	v_mul_f32_e32 v82, 0x3d372713, v80
	v_mul_f32_e32 v82, v80, v82
	v_fma_f32 v82, v80, v82, v80
	v_mul_f32_e32 v82, 0x3f4c422a, v82
	v_add_f32_e32 v82, v82, v82
	v_mul_f32_e32 v82, 0x3fb8aa3b, v82
	v_exp_f32_e32 v82, v82
	v_mul_f32_e32 v80, 0.5, v80
	v_add_f32_e32 v82, 1.0, v82
	v_div_scale_f32 v83, s[28:29], v82, v82, 2.0
	v_rcp_f32_e32 v84, v83
	s_nop 0
	v_fma_f32 v85, -v83, v84, 1.0
	v_fmac_f32_e32 v84, v85, v84
	v_div_scale_f32 v85, vcc, 2.0, v82, 2.0
	v_mul_f32_e32 v86, v85, v84
	v_fma_f32 v87, -v83, v86, v85
	v_fmac_f32_e32 v86, v87, v84
	v_fma_f32 v83, -v83, v86, v85
	v_div_fmas_f32 v83, v83, v84, v86
	v_div_fixup_f32 v82, v83, v82, 2.0
	v_sub_f32_e32 v82, 1.0, v82
	v_add_f32_e32 v82, 1.0, v82
	v_mul_f32_e32 v82, v80, v82
	v_mul_f32_e32 v80, 0x3d372713, v81
	v_mul_f32_e32 v80, v81, v80
	v_fma_f32 v80, v81, v80, v81
	v_mul_f32_e32 v80, 0x3f4c422a, v80
	v_add_f32_e32 v80, v80, v80
	v_mul_f32_e32 v80, 0x3fb8aa3b, v80
	v_exp_f32_e32 v80, v80
	v_mul_f32_e32 v81, 0.5, v81
	v_add_f32_e32 v80, 1.0, v80
	v_div_scale_f32 v83, s[28:29], v80, v80, 2.0
	v_rcp_f32_e32 v84, v83
	s_nop 0
	v_fma_f32 v85, -v83, v84, 1.0
	v_fmac_f32_e32 v84, v85, v84
	v_div_scale_f32 v85, vcc, 2.0, v80, 2.0
	v_mul_f32_e32 v86, v85, v84
	v_fma_f32 v87, -v83, v86, v85
	v_fmac_f32_e32 v86, v87, v84
	v_fma_f32 v83, -v83, v86, v85
	v_div_fmas_f32 v83, v83, v84, v86
	v_div_fixup_f32 v80, v83, v80, 2.0
	v_sub_f32_e32 v80, 1.0, v80
	v_add_f32_e32 v80, 1.0, v80
	v_mul_f32_e32 v81, v81, v80
	v_cvt_pk_bf16_f32 v192, v78, v79
	v_lshl_add_u64 v[78:79], s[26:27], 0, v[148:149]
	v_lshl_add_u64 v[78:79], v[78:79], 0, v[140:141]
	v_cvt_pk_bf16_f32 v193, v82, v81
	s_nop 0
	v_mov_b64_e32 v[80:81], v[180:181]
	v_mov_b64_e32 v[82:83], v[182:183]
	s_nop 0
	v_pk_add_f32 v[74:75], v[74:75], v[80:81]
	s_nop 0
	v_mul_f32_e32 v80, 0x3d372713, v74
	v_mul_f32_e32 v80, v74, v80
	v_fma_f32 v80, v74, v80, v74
	v_mul_f32_e32 v80, 0x3f4c422a, v80
	v_add_f32_e32 v80, v80, v80
	v_mul_f32_e32 v80, 0x3fb8aa3b, v80
	v_exp_f32_e32 v80, v80
	v_pk_add_f32 v[76:77], v[76:77], v[82:83]
	v_mul_f32_e32 v74, 0.5, v74
	v_add_f32_e32 v80, 1.0, v80
	v_div_scale_f32 v81, s[28:29], v80, v80, 2.0
	v_rcp_f32_e32 v82, v81
	s_nop 0
	v_fma_f32 v83, -v81, v82, 1.0
	v_fmac_f32_e32 v82, v83, v82
	v_div_scale_f32 v83, vcc, 2.0, v80, 2.0
	v_mul_f32_e32 v84, v83, v82
	v_fma_f32 v85, -v81, v84, v83
	v_fmac_f32_e32 v84, v85, v82
	v_fma_f32 v81, -v81, v84, v83
	v_div_fmas_f32 v81, v81, v82, v84
	v_div_fixup_f32 v80, v81, v80, 2.0
	v_sub_f32_e32 v80, 1.0, v80
	v_add_f32_e32 v80, 1.0, v80
	v_mul_f32_e32 v74, v74, v80
	v_mul_f32_e32 v80, 0x3d372713, v75
	v_mul_f32_e32 v80, v75, v80
	v_fma_f32 v80, v75, v80, v75
	v_mul_f32_e32 v80, 0x3f4c422a, v80
	v_add_f32_e32 v80, v80, v80
	v_mul_f32_e32 v80, 0x3fb8aa3b, v80
	v_exp_f32_e32 v80, v80
	v_mul_f32_e32 v75, 0.5, v75
	v_add_f32_e32 v80, 1.0, v80
	v_div_scale_f32 v81, s[28:29], v80, v80, 2.0
	v_rcp_f32_e32 v82, v81
	s_nop 0
	v_fma_f32 v83, -v81, v82, 1.0
	v_fmac_f32_e32 v82, v83, v82
	v_div_scale_f32 v83, vcc, 2.0, v80, 2.0
	v_mul_f32_e32 v84, v83, v82
	v_fma_f32 v85, -v81, v84, v83
	v_fmac_f32_e32 v84, v85, v82
	v_fma_f32 v81, -v81, v84, v83
	v_div_fmas_f32 v81, v81, v82, v84
	v_div_fixup_f32 v80, v81, v80, 2.0
	v_sub_f32_e32 v80, 1.0, v80
	v_add_f32_e32 v80, 1.0, v80
	v_mul_f32_e32 v75, v75, v80
	v_mul_f32_e32 v80, 0x3d372713, v76
	v_mul_f32_e32 v80, v76, v80
	v_fma_f32 v80, v76, v80, v76
	v_mul_f32_e32 v80, 0x3f4c422a, v80
	v_add_f32_e32 v80, v80, v80
	v_mul_f32_e32 v80, 0x3fb8aa3b, v80
	v_exp_f32_e32 v80, v80
	v_mul_f32_e32 v76, 0.5, v76
	v_cvt_pk_bf16_f32 v194, v74, v75
	v_add_f32_e32 v80, 1.0, v80
	v_div_scale_f32 v81, s[28:29], v80, v80, 2.0
	v_rcp_f32_e32 v82, v81
	s_nop 0
	v_fma_f32 v83, -v81, v82, 1.0
	v_fmac_f32_e32 v82, v83, v82
	v_div_scale_f32 v83, vcc, 2.0, v80, 2.0
	v_mul_f32_e32 v84, v83, v82
	v_fma_f32 v85, -v81, v84, v83
	v_fmac_f32_e32 v84, v85, v82
	v_fma_f32 v81, -v81, v84, v83
	v_div_fmas_f32 v81, v81, v82, v84
	v_div_fixup_f32 v80, v81, v80, 2.0
	v_sub_f32_e32 v80, 1.0, v80
	v_add_f32_e32 v80, 1.0, v80
	v_mul_f32_e32 v76, v76, v80
	v_mul_f32_e32 v80, 0x3d372713, v77
	v_mul_f32_e32 v80, v77, v80
	v_fma_f32 v80, v77, v80, v77
	v_mul_f32_e32 v80, 0x3f4c422a, v80
	v_add_f32_e32 v80, v80, v80
	v_mul_f32_e32 v80, 0x3fb8aa3b, v80
	v_exp_f32_e32 v80, v80
	v_mul_f32_e32 v77, 0.5, v77
	v_add_f32_e32 v80, 1.0, v80
	v_div_scale_f32 v81, s[28:29], v80, v80, 2.0
	v_rcp_f32_e32 v82, v81
	s_nop 0
	v_fma_f32 v83, -v81, v82, 1.0
	v_fmac_f32_e32 v82, v83, v82
	v_div_scale_f32 v83, vcc, 2.0, v80, 2.0
	v_mul_f32_e32 v84, v83, v82
	v_fma_f32 v85, -v81, v84, v83
	v_fmac_f32_e32 v84, v85, v82
	v_fma_f32 v81, -v81, v84, v83
	v_div_fmas_f32 v81, v81, v82, v84
	v_div_fixup_f32 v80, v81, v80, 2.0
	v_sub_f32_e32 v80, 1.0, v80
	v_add_f32_e32 v80, 1.0, v80
	v_mul_f32_e32 v77, v77, v80
	v_cvt_pk_bf16_f32 v195, v76, v77
	s_nop 1
	v_permlane16_swap_b32_e32 v192, v194
	v_permlane16_swap_b32_e32 v193, v195
	v_lshl_add_u64 v[200:201], v[78:79], 0, v[202:203]
	global_store_dwordx4 v[200:201], v[192:195], off
	v_mov_b64_e32 v[74:75], v[184:185]
	v_mov_b64_e32 v[76:77], v[186:187]
	s_nop 0
	v_pk_add_f32 v[70:71], v[70:71], v[74:75]
	s_nop 0
	v_mul_f32_e32 v74, 0x3d372713, v70
	v_mul_f32_e32 v74, v70, v74
	v_fma_f32 v74, v70, v74, v70
	v_mul_f32_e32 v74, 0x3f4c422a, v74
	v_add_f32_e32 v74, v74, v74
	v_mul_f32_e32 v74, 0x3fb8aa3b, v74
	v_exp_f32_e32 v74, v74
	v_pk_add_f32 v[72:73], v[72:73], v[76:77]
	v_mul_f32_e32 v70, 0.5, v70
	v_add_f32_e32 v74, 1.0, v74
	v_div_scale_f32 v75, s[28:29], v74, v74, 2.0
	v_rcp_f32_e32 v76, v75
	s_nop 0
	v_fma_f32 v77, -v75, v76, 1.0
	v_fmac_f32_e32 v76, v77, v76
	v_div_scale_f32 v77, vcc, 2.0, v74, 2.0
	v_mul_f32_e32 v80, v77, v76
	v_fma_f32 v81, -v75, v80, v77
	v_fmac_f32_e32 v80, v81, v76
	v_fma_f32 v75, -v75, v80, v77
	v_div_fmas_f32 v75, v75, v76, v80
	v_div_fixup_f32 v74, v75, v74, 2.0
	v_sub_f32_e32 v74, 1.0, v74
	v_add_f32_e32 v74, 1.0, v74
	v_mul_f32_e32 v70, v70, v74
	v_mul_f32_e32 v74, 0x3d372713, v71
	v_mul_f32_e32 v74, v71, v74
	v_fma_f32 v74, v71, v74, v71
	v_mul_f32_e32 v74, 0x3f4c422a, v74
	v_add_f32_e32 v74, v74, v74
	v_mul_f32_e32 v74, 0x3fb8aa3b, v74
	v_exp_f32_e32 v74, v74
	v_mul_f32_e32 v71, 0.5, v71
	v_add_f32_e32 v74, 1.0, v74
	v_div_scale_f32 v75, s[28:29], v74, v74, 2.0
	v_rcp_f32_e32 v76, v75
	s_nop 0
	v_fma_f32 v77, -v75, v76, 1.0
	v_fmac_f32_e32 v76, v77, v76
	v_div_scale_f32 v77, vcc, 2.0, v74, 2.0
	v_mul_f32_e32 v80, v77, v76
	v_fma_f32 v81, -v75, v80, v77
	v_fmac_f32_e32 v80, v81, v76
	v_fma_f32 v75, -v75, v80, v77
	v_div_fmas_f32 v75, v75, v76, v80
	v_div_fixup_f32 v74, v75, v74, 2.0
	v_sub_f32_e32 v74, 1.0, v74
	v_add_f32_e32 v74, 1.0, v74
	v_mul_f32_e32 v71, v71, v74
	v_mul_f32_e32 v74, 0x3d372713, v72
	v_mul_f32_e32 v74, v72, v74
	v_fma_f32 v74, v72, v74, v72
	v_mul_f32_e32 v74, 0x3f4c422a, v74
	v_add_f32_e32 v74, v74, v74
	v_mul_f32_e32 v74, 0x3fb8aa3b, v74
	v_exp_f32_e32 v74, v74
	v_mul_f32_e32 v72, 0.5, v72
	v_cvt_pk_bf16_f32 v196, v70, v71
	v_add_f32_e32 v74, 1.0, v74
	v_div_scale_f32 v75, s[28:29], v74, v74, 2.0
	v_rcp_f32_e32 v76, v75
	s_nop 0
	v_fma_f32 v77, -v75, v76, 1.0
	v_fmac_f32_e32 v76, v77, v76
	v_div_scale_f32 v77, vcc, 2.0, v74, 2.0
	v_mul_f32_e32 v80, v77, v76
	v_fma_f32 v81, -v75, v80, v77
	v_fmac_f32_e32 v80, v81, v76
	v_fma_f32 v75, -v75, v80, v77
	v_div_fmas_f32 v75, v75, v76, v80
	v_div_fixup_f32 v74, v75, v74, 2.0
	v_sub_f32_e32 v74, 1.0, v74
	v_add_f32_e32 v74, 1.0, v74
	v_mul_f32_e32 v72, v72, v74
	v_mul_f32_e32 v74, 0x3d372713, v73
	v_mul_f32_e32 v74, v73, v74
	v_fma_f32 v74, v73, v74, v73
	v_mul_f32_e32 v74, 0x3f4c422a, v74
	v_add_f32_e32 v74, v74, v74
	v_mul_f32_e32 v74, 0x3fb8aa3b, v74
	v_exp_f32_e32 v74, v74
	v_mul_f32_e32 v73, 0.5, v73
	v_add_f32_e32 v74, 1.0, v74
	v_div_scale_f32 v75, s[28:29], v74, v74, 2.0
	v_rcp_f32_e32 v76, v75
	s_nop 0
	v_fma_f32 v77, -v75, v76, 1.0
	v_fmac_f32_e32 v76, v77, v76
	v_div_scale_f32 v77, vcc, 2.0, v74, 2.0
	v_mul_f32_e32 v80, v77, v76
	v_fma_f32 v81, -v75, v80, v77
	v_fmac_f32_e32 v80, v81, v76
	v_fma_f32 v75, -v75, v80, v77
	v_div_fmas_f32 v75, v75, v76, v80
	v_div_fixup_f32 v74, v75, v74, 2.0
	v_sub_f32_e32 v74, 1.0, v74
	v_add_f32_e32 v74, 1.0, v74
	v_mul_f32_e32 v73, v73, v74
	v_cvt_pk_bf16_f32 v197, v72, v73
	s_nop 0
	v_mov_b64_e32 v[70:71], v[188:189]
	v_mov_b64_e32 v[72:73], v[190:191]
	s_nop 0
	v_pk_add_f32 v[66:67], v[66:67], v[70:71]
	s_nop 0
	v_mul_f32_e32 v70, 0x3d372713, v66
	v_mul_f32_e32 v70, v66, v70
	v_fma_f32 v70, v66, v70, v66
	v_mul_f32_e32 v70, 0x3f4c422a, v70
	v_add_f32_e32 v70, v70, v70
	v_mul_f32_e32 v70, 0x3fb8aa3b, v70
	v_exp_f32_e32 v70, v70
	v_pk_add_f32 v[68:69], v[68:69], v[72:73]
	v_mul_f32_e32 v66, 0.5, v66
	v_add_f32_e32 v70, 1.0, v70
	v_div_scale_f32 v71, s[28:29], v70, v70, 2.0
	v_rcp_f32_e32 v72, v71
	s_nop 0
	v_fma_f32 v73, -v71, v72, 1.0
	v_fmac_f32_e32 v72, v73, v72
	v_div_scale_f32 v73, vcc, 2.0, v70, 2.0
	v_mul_f32_e32 v74, v73, v72
	v_fma_f32 v75, -v71, v74, v73
	v_fmac_f32_e32 v74, v75, v72
	v_fma_f32 v71, -v71, v74, v73
	v_div_fmas_f32 v71, v71, v72, v74
	v_div_fixup_f32 v70, v71, v70, 2.0
	v_sub_f32_e32 v70, 1.0, v70
	v_add_f32_e32 v70, 1.0, v70
	v_mul_f32_e32 v66, v66, v70
	v_mul_f32_e32 v70, 0x3d372713, v67
	v_mul_f32_e32 v70, v67, v70
	v_fma_f32 v70, v67, v70, v67
	v_mul_f32_e32 v70, 0x3f4c422a, v70
	v_add_f32_e32 v70, v70, v70
	v_mul_f32_e32 v70, 0x3fb8aa3b, v70
	v_exp_f32_e32 v70, v70
	v_mul_f32_e32 v67, 0.5, v67
	v_add_f32_e32 v70, 1.0, v70
	v_div_scale_f32 v71, s[28:29], v70, v70, 2.0
	v_rcp_f32_e32 v72, v71
	s_nop 0
	v_fma_f32 v73, -v71, v72, 1.0
	v_fmac_f32_e32 v72, v73, v72
	v_div_scale_f32 v73, vcc, 2.0, v70, 2.0
	v_mul_f32_e32 v74, v73, v72
	v_fma_f32 v75, -v71, v74, v73
	v_fmac_f32_e32 v74, v75, v72
	v_fma_f32 v71, -v71, v74, v73
	v_div_fmas_f32 v71, v71, v72, v74
	v_div_fixup_f32 v70, v71, v70, 2.0
	v_sub_f32_e32 v70, 1.0, v70
	v_add_f32_e32 v70, 1.0, v70
	v_mul_f32_e32 v67, v67, v70
	v_mul_f32_e32 v70, 0x3d372713, v68
	v_mul_f32_e32 v70, v68, v70
	v_fma_f32 v70, v68, v70, v68
	v_mul_f32_e32 v70, 0x3f4c422a, v70
	v_add_f32_e32 v70, v70, v70
	v_mul_f32_e32 v70, 0x3fb8aa3b, v70
	v_exp_f32_e32 v70, v70
	v_mul_f32_e32 v68, 0.5, v68
	v_cvt_pk_bf16_f32 v198, v66, v67
	v_add_f32_e32 v70, 1.0, v70
	v_div_scale_f32 v71, s[28:29], v70, v70, 2.0
	v_rcp_f32_e32 v72, v71
	s_nop 0
	v_fma_f32 v73, -v71, v72, 1.0
	v_fmac_f32_e32 v72, v73, v72
	v_div_scale_f32 v73, vcc, 2.0, v70, 2.0
	v_mul_f32_e32 v74, v73, v72
	v_fma_f32 v75, -v71, v74, v73
	v_fmac_f32_e32 v74, v75, v72
	v_fma_f32 v71, -v71, v74, v73
	v_div_fmas_f32 v71, v71, v72, v74
	v_div_fixup_f32 v70, v71, v70, 2.0
	v_sub_f32_e32 v70, 1.0, v70
	v_add_f32_e32 v70, 1.0, v70
	v_mul_f32_e32 v68, v68, v70
	v_mul_f32_e32 v70, 0x3d372713, v69
	v_mul_f32_e32 v70, v69, v70
	v_fma_f32 v70, v69, v70, v69
	v_mul_f32_e32 v70, 0x3f4c422a, v70
	v_add_f32_e32 v70, v70, v70
	v_mul_f32_e32 v70, 0x3fb8aa3b, v70
	v_exp_f32_e32 v70, v70
	v_mul_f32_e32 v69, 0.5, v69
	v_add_f32_e32 v70, 1.0, v70
	v_div_scale_f32 v71, s[28:29], v70, v70, 2.0
	v_rcp_f32_e32 v72, v71
	s_nop 0
	v_fma_f32 v73, -v71, v72, 1.0
	v_fmac_f32_e32 v72, v73, v72
	v_div_scale_f32 v73, vcc, 2.0, v70, 2.0
	v_mul_f32_e32 v74, v73, v72
	v_fma_f32 v75, -v71, v74, v73
	v_fmac_f32_e32 v74, v75, v72
	v_fma_f32 v71, -v71, v74, v73
	v_div_fmas_f32 v71, v71, v72, v74
	v_div_fixup_f32 v70, v71, v70, 2.0
	v_sub_f32_e32 v70, 1.0, v70
	v_add_f32_e32 v70, 1.0, v70
	v_mul_f32_e32 v69, v69, v70
	v_cvt_pk_bf16_f32 v199, v68, v69
	s_nop 1
	v_permlane16_swap_b32_e32 v196, v198
	v_permlane16_swap_b32_e32 v197, v199
	v_lshl_add_u64 v[200:201], v[78:79], 0, v[202:203]
	global_store_dwordx4 v[200:201], v[196:199], off offset:256
	v_mov_b64_e32 v[66:67], v[176:177]
	v_mov_b64_e32 v[68:69], v[178:179]
	s_nop 0
	v_pk_add_f32 v[62:63], v[62:63], v[66:67]
	s_nop 0
	v_mul_f32_e32 v66, 0x3d372713, v62
	v_mul_f32_e32 v66, v62, v66
	v_fma_f32 v66, v62, v66, v62
	v_mul_f32_e32 v66, 0x3f4c422a, v66
	v_add_f32_e32 v66, v66, v66
	v_mul_f32_e32 v66, 0x3fb8aa3b, v66
	v_exp_f32_e32 v66, v66
	v_pk_add_f32 v[64:65], v[64:65], v[68:69]
	v_mul_f32_e32 v62, 0.5, v62
	v_add_f32_e32 v66, 1.0, v66
	v_div_scale_f32 v67, s[28:29], v66, v66, 2.0
	v_rcp_f32_e32 v68, v67
	s_nop 0
	v_fma_f32 v69, -v67, v68, 1.0
	v_fmac_f32_e32 v68, v69, v68
	v_div_scale_f32 v69, vcc, 2.0, v66, 2.0
	v_mul_f32_e32 v70, v69, v68
	v_fma_f32 v71, -v67, v70, v69
	v_fmac_f32_e32 v70, v71, v68
	v_fma_f32 v67, -v67, v70, v69
	v_div_fmas_f32 v67, v67, v68, v70
	v_div_fixup_f32 v66, v67, v66, 2.0
	v_sub_f32_e32 v66, 1.0, v66
	v_add_f32_e32 v66, 1.0, v66
	v_mul_f32_e32 v62, v62, v66
	v_mul_f32_e32 v66, 0x3d372713, v63
	v_mul_f32_e32 v66, v63, v66
	v_fma_f32 v66, v63, v66, v63
	v_mul_f32_e32 v66, 0x3f4c422a, v66
	v_add_f32_e32 v66, v66, v66
	v_mul_f32_e32 v66, 0x3fb8aa3b, v66
	v_exp_f32_e32 v66, v66
	v_mul_f32_e32 v63, 0.5, v63
	v_add_f32_e32 v66, 1.0, v66
	v_div_scale_f32 v67, s[28:29], v66, v66, 2.0
	v_rcp_f32_e32 v68, v67
	s_nop 0
	v_fma_f32 v69, -v67, v68, 1.0
	v_fmac_f32_e32 v68, v69, v68
	v_div_scale_f32 v69, vcc, 2.0, v66, 2.0
	v_mul_f32_e32 v70, v69, v68
	v_fma_f32 v71, -v67, v70, v69
	v_fmac_f32_e32 v70, v71, v68
	v_fma_f32 v67, -v67, v70, v69
	v_div_fmas_f32 v67, v67, v68, v70
	v_div_fixup_f32 v66, v67, v66, 2.0
	v_sub_f32_e32 v66, 1.0, v66
	v_add_f32_e32 v66, 1.0, v66
	v_mul_f32_e32 v63, v63, v66
	v_mul_f32_e32 v66, 0x3d372713, v64
	v_mul_f32_e32 v66, v64, v66
	v_fma_f32 v66, v64, v66, v64
	v_mul_f32_e32 v66, 0x3f4c422a, v66
	v_add_f32_e32 v66, v66, v66
	v_mul_f32_e32 v66, 0x3fb8aa3b, v66
	v_exp_f32_e32 v66, v66
	v_mul_f32_e32 v64, 0.5, v64
	v_add_f32_e32 v66, 1.0, v66
	v_div_scale_f32 v67, s[28:29], v66, v66, 2.0
	v_rcp_f32_e32 v68, v67
	s_nop 0
	v_fma_f32 v69, -v67, v68, 1.0
	v_fmac_f32_e32 v68, v69, v68
	v_div_scale_f32 v69, vcc, 2.0, v66, 2.0
	v_mul_f32_e32 v70, v69, v68
	v_fma_f32 v71, -v67, v70, v69
	v_fmac_f32_e32 v70, v71, v68
	v_fma_f32 v67, -v67, v70, v69
	v_div_fmas_f32 v67, v67, v68, v70
	v_div_fixup_f32 v66, v67, v66, 2.0
	v_sub_f32_e32 v66, 1.0, v66
	v_add_f32_e32 v66, 1.0, v66
	v_mul_f32_e32 v66, v64, v66
	v_mul_f32_e32 v64, 0x3d372713, v65
	v_mul_f32_e32 v64, v65, v64
	v_fma_f32 v64, v65, v64, v65
	v_mul_f32_e32 v64, 0x3f4c422a, v64
	v_add_f32_e32 v64, v64, v64
	v_mul_f32_e32 v64, 0x3fb8aa3b, v64
	v_exp_f32_e32 v64, v64
	v_mul_f32_e32 v65, 0.5, v65
	v_add_f32_e32 v64, 1.0, v64
	v_div_scale_f32 v67, s[28:29], v64, v64, 2.0
	v_rcp_f32_e32 v68, v67
	s_nop 0
	v_fma_f32 v69, -v67, v68, 1.0
	v_fmac_f32_e32 v68, v69, v68
	v_div_scale_f32 v69, vcc, 2.0, v64, 2.0
	v_mul_f32_e32 v70, v69, v68
	v_fma_f32 v71, -v67, v70, v69
	v_fmac_f32_e32 v70, v71, v68
	v_fma_f32 v67, -v67, v70, v69
	v_div_fmas_f32 v67, v67, v68, v70
	v_div_fixup_f32 v64, v67, v64, 2.0
	v_sub_f32_e32 v64, 1.0, v64
	v_add_f32_e32 v64, 1.0, v64
	v_mul_f32_e32 v65, v65, v64
	v_cvt_pk_bf16_f32 v192, v62, v63
	v_lshl_add_u64 v[62:63], s[26:27], 0, v[150:151]
	v_lshl_add_u64 v[62:63], v[62:63], 0, v[140:141]
	v_cvt_pk_bf16_f32 v193, v66, v65
	s_nop 0
	v_mov_b64_e32 v[64:65], v[180:181]
	v_mov_b64_e32 v[66:67], v[182:183]
	s_nop 0
	v_pk_add_f32 v[58:59], v[58:59], v[64:65]
	s_nop 0
	v_mul_f32_e32 v64, 0x3d372713, v58
	v_mul_f32_e32 v64, v58, v64
	v_fma_f32 v64, v58, v64, v58
	v_mul_f32_e32 v64, 0x3f4c422a, v64
	v_add_f32_e32 v64, v64, v64
	v_mul_f32_e32 v64, 0x3fb8aa3b, v64
	v_exp_f32_e32 v64, v64
	v_pk_add_f32 v[60:61], v[60:61], v[66:67]
	v_mul_f32_e32 v58, 0.5, v58
	v_add_f32_e32 v64, 1.0, v64
	v_div_scale_f32 v65, s[28:29], v64, v64, 2.0
	v_rcp_f32_e32 v66, v65
	s_nop 0
	v_fma_f32 v67, -v65, v66, 1.0
	v_fmac_f32_e32 v66, v67, v66
	v_div_scale_f32 v67, vcc, 2.0, v64, 2.0
	v_mul_f32_e32 v68, v67, v66
	v_fma_f32 v69, -v65, v68, v67
	v_fmac_f32_e32 v68, v69, v66
	v_fma_f32 v65, -v65, v68, v67
	v_div_fmas_f32 v65, v65, v66, v68
	v_div_fixup_f32 v64, v65, v64, 2.0
	v_sub_f32_e32 v64, 1.0, v64
	v_add_f32_e32 v64, 1.0, v64
	v_mul_f32_e32 v58, v58, v64
	v_mul_f32_e32 v64, 0x3d372713, v59
	v_mul_f32_e32 v64, v59, v64
	v_fma_f32 v64, v59, v64, v59
	v_mul_f32_e32 v64, 0x3f4c422a, v64
	v_add_f32_e32 v64, v64, v64
	v_mul_f32_e32 v64, 0x3fb8aa3b, v64
	v_exp_f32_e32 v64, v64
	v_mul_f32_e32 v59, 0.5, v59
	v_add_f32_e32 v64, 1.0, v64
	v_div_scale_f32 v65, s[28:29], v64, v64, 2.0
	v_rcp_f32_e32 v66, v65
	s_nop 0
	v_fma_f32 v67, -v65, v66, 1.0
	v_fmac_f32_e32 v66, v67, v66
	v_div_scale_f32 v67, vcc, 2.0, v64, 2.0
	v_mul_f32_e32 v68, v67, v66
	v_fma_f32 v69, -v65, v68, v67
	v_fmac_f32_e32 v68, v69, v66
	v_fma_f32 v65, -v65, v68, v67
	v_div_fmas_f32 v65, v65, v66, v68
	v_div_fixup_f32 v64, v65, v64, 2.0
	v_sub_f32_e32 v64, 1.0, v64
	v_add_f32_e32 v64, 1.0, v64
	v_mul_f32_e32 v59, v59, v64
	v_mul_f32_e32 v64, 0x3d372713, v60
	v_mul_f32_e32 v64, v60, v64
	v_fma_f32 v64, v60, v64, v60
	v_mul_f32_e32 v64, 0x3f4c422a, v64
	v_add_f32_e32 v64, v64, v64
	v_mul_f32_e32 v64, 0x3fb8aa3b, v64
	v_exp_f32_e32 v64, v64
	v_mul_f32_e32 v60, 0.5, v60
	v_cvt_pk_bf16_f32 v194, v58, v59
	v_add_f32_e32 v64, 1.0, v64
	v_div_scale_f32 v65, s[28:29], v64, v64, 2.0
	v_rcp_f32_e32 v66, v65
	s_nop 0
	v_fma_f32 v67, -v65, v66, 1.0
	v_fmac_f32_e32 v66, v67, v66
	v_div_scale_f32 v67, vcc, 2.0, v64, 2.0
	v_mul_f32_e32 v68, v67, v66
	v_fma_f32 v69, -v65, v68, v67
	v_fmac_f32_e32 v68, v69, v66
	v_fma_f32 v65, -v65, v68, v67
	v_div_fmas_f32 v65, v65, v66, v68
	v_div_fixup_f32 v64, v65, v64, 2.0
	v_sub_f32_e32 v64, 1.0, v64
	v_add_f32_e32 v64, 1.0, v64
	v_mul_f32_e32 v60, v60, v64
	v_mul_f32_e32 v64, 0x3d372713, v61
	v_mul_f32_e32 v64, v61, v64
	v_fma_f32 v64, v61, v64, v61
	v_mul_f32_e32 v64, 0x3f4c422a, v64
	v_add_f32_e32 v64, v64, v64
	v_mul_f32_e32 v64, 0x3fb8aa3b, v64
	v_exp_f32_e32 v64, v64
	v_mul_f32_e32 v61, 0.5, v61
	v_add_f32_e32 v64, 1.0, v64
	v_div_scale_f32 v65, s[28:29], v64, v64, 2.0
	v_rcp_f32_e32 v66, v65
	s_nop 0
	v_fma_f32 v67, -v65, v66, 1.0
	v_fmac_f32_e32 v66, v67, v66
	v_div_scale_f32 v67, vcc, 2.0, v64, 2.0
	v_mul_f32_e32 v68, v67, v66
	v_fma_f32 v69, -v65, v68, v67
	v_fmac_f32_e32 v68, v69, v66
	v_fma_f32 v65, -v65, v68, v67
	v_div_fmas_f32 v65, v65, v66, v68
	v_div_fixup_f32 v64, v65, v64, 2.0
	v_sub_f32_e32 v64, 1.0, v64
	v_add_f32_e32 v64, 1.0, v64
	v_mul_f32_e32 v61, v61, v64
	v_cvt_pk_bf16_f32 v195, v60, v61
	s_nop 1
	v_permlane16_swap_b32_e32 v192, v194
	v_permlane16_swap_b32_e32 v193, v195
	v_lshl_add_u64 v[200:201], v[62:63], 0, v[202:203]
	global_store_dwordx4 v[200:201], v[192:195], off
	v_mov_b64_e32 v[58:59], v[184:185]
	v_mov_b64_e32 v[60:61], v[186:187]
	s_nop 0
	v_pk_add_f32 v[54:55], v[54:55], v[58:59]
	s_nop 0
	v_mul_f32_e32 v58, 0x3d372713, v54
	v_mul_f32_e32 v58, v54, v58
	v_fma_f32 v58, v54, v58, v54
	v_mul_f32_e32 v58, 0x3f4c422a, v58
	v_add_f32_e32 v58, v58, v58
	v_mul_f32_e32 v58, 0x3fb8aa3b, v58
	v_exp_f32_e32 v58, v58
	v_pk_add_f32 v[56:57], v[56:57], v[60:61]
	v_mul_f32_e32 v54, 0.5, v54
	v_add_f32_e32 v58, 1.0, v58
	v_div_scale_f32 v59, s[28:29], v58, v58, 2.0
	v_rcp_f32_e32 v60, v59
	s_nop 0
	v_fma_f32 v61, -v59, v60, 1.0
	v_fmac_f32_e32 v60, v61, v60
	v_div_scale_f32 v61, vcc, 2.0, v58, 2.0
	v_mul_f32_e32 v64, v61, v60
	v_fma_f32 v65, -v59, v64, v61
	v_fmac_f32_e32 v64, v65, v60
	v_fma_f32 v59, -v59, v64, v61
	v_div_fmas_f32 v59, v59, v60, v64
	v_div_fixup_f32 v58, v59, v58, 2.0
	v_sub_f32_e32 v58, 1.0, v58
	v_add_f32_e32 v58, 1.0, v58
	v_mul_f32_e32 v54, v54, v58
	v_mul_f32_e32 v58, 0x3d372713, v55
	v_mul_f32_e32 v58, v55, v58
	v_fma_f32 v58, v55, v58, v55
	v_mul_f32_e32 v58, 0x3f4c422a, v58
	v_add_f32_e32 v58, v58, v58
	v_mul_f32_e32 v58, 0x3fb8aa3b, v58
	v_exp_f32_e32 v58, v58
	v_mul_f32_e32 v55, 0.5, v55
	v_add_f32_e32 v58, 1.0, v58
	v_div_scale_f32 v59, s[28:29], v58, v58, 2.0
	v_rcp_f32_e32 v60, v59
	s_nop 0
	v_fma_f32 v61, -v59, v60, 1.0
	v_fmac_f32_e32 v60, v61, v60
	v_div_scale_f32 v61, vcc, 2.0, v58, 2.0
	v_mul_f32_e32 v64, v61, v60
	v_fma_f32 v65, -v59, v64, v61
	v_fmac_f32_e32 v64, v65, v60
	v_fma_f32 v59, -v59, v64, v61
	v_div_fmas_f32 v59, v59, v60, v64
	v_div_fixup_f32 v58, v59, v58, 2.0
	v_sub_f32_e32 v58, 1.0, v58
	v_add_f32_e32 v58, 1.0, v58
	v_mul_f32_e32 v55, v55, v58
	v_mul_f32_e32 v58, 0x3d372713, v56
	v_mul_f32_e32 v58, v56, v58
	v_fma_f32 v58, v56, v58, v56
	v_mul_f32_e32 v58, 0x3f4c422a, v58
	v_add_f32_e32 v58, v58, v58
	v_mul_f32_e32 v58, 0x3fb8aa3b, v58
	v_exp_f32_e32 v58, v58
	v_mul_f32_e32 v56, 0.5, v56
	v_cvt_pk_bf16_f32 v196, v54, v55
	v_add_f32_e32 v58, 1.0, v58
	v_div_scale_f32 v59, s[28:29], v58, v58, 2.0
	v_rcp_f32_e32 v60, v59
	s_nop 0
	v_fma_f32 v61, -v59, v60, 1.0
	v_fmac_f32_e32 v60, v61, v60
	v_div_scale_f32 v61, vcc, 2.0, v58, 2.0
	v_mul_f32_e32 v64, v61, v60
	v_fma_f32 v65, -v59, v64, v61
	v_fmac_f32_e32 v64, v65, v60
	v_fma_f32 v59, -v59, v64, v61
	v_div_fmas_f32 v59, v59, v60, v64
	v_div_fixup_f32 v58, v59, v58, 2.0
	v_sub_f32_e32 v58, 1.0, v58
	v_add_f32_e32 v58, 1.0, v58
	v_mul_f32_e32 v56, v56, v58
	v_mul_f32_e32 v58, 0x3d372713, v57
	v_mul_f32_e32 v58, v57, v58
	v_fma_f32 v58, v57, v58, v57
	v_mul_f32_e32 v58, 0x3f4c422a, v58
	v_add_f32_e32 v58, v58, v58
	v_mul_f32_e32 v58, 0x3fb8aa3b, v58
	v_exp_f32_e32 v58, v58
	v_mul_f32_e32 v57, 0.5, v57
	v_add_f32_e32 v58, 1.0, v58
	v_div_scale_f32 v59, s[28:29], v58, v58, 2.0
	v_rcp_f32_e32 v60, v59
	s_nop 0
	v_fma_f32 v61, -v59, v60, 1.0
	v_fmac_f32_e32 v60, v61, v60
	v_div_scale_f32 v61, vcc, 2.0, v58, 2.0
	v_mul_f32_e32 v64, v61, v60
	v_fma_f32 v65, -v59, v64, v61
	v_fmac_f32_e32 v64, v65, v60
	v_fma_f32 v59, -v59, v64, v61
	v_div_fmas_f32 v59, v59, v60, v64
	v_div_fixup_f32 v58, v59, v58, 2.0
	v_sub_f32_e32 v58, 1.0, v58
	v_add_f32_e32 v58, 1.0, v58
	v_mul_f32_e32 v57, v57, v58
	v_cvt_pk_bf16_f32 v197, v56, v57
	s_nop 0
	v_mov_b64_e32 v[54:55], v[188:189]
	v_mov_b64_e32 v[56:57], v[190:191]
	s_nop 0
	v_pk_add_f32 v[50:51], v[50:51], v[54:55]
	s_nop 0
	v_mul_f32_e32 v54, 0x3d372713, v50
	v_mul_f32_e32 v54, v50, v54
	v_fma_f32 v54, v50, v54, v50
	v_mul_f32_e32 v54, 0x3f4c422a, v54
	v_add_f32_e32 v54, v54, v54
	v_mul_f32_e32 v54, 0x3fb8aa3b, v54
	v_exp_f32_e32 v54, v54
	v_pk_add_f32 v[52:53], v[52:53], v[56:57]
	v_mul_f32_e32 v50, 0.5, v50
	v_add_f32_e32 v54, 1.0, v54
	v_div_scale_f32 v55, s[28:29], v54, v54, 2.0
	v_rcp_f32_e32 v56, v55
	s_nop 0
	v_fma_f32 v57, -v55, v56, 1.0
	v_fmac_f32_e32 v56, v57, v56
	v_div_scale_f32 v57, vcc, 2.0, v54, 2.0
	v_mul_f32_e32 v58, v57, v56
	v_fma_f32 v59, -v55, v58, v57
	v_fmac_f32_e32 v58, v59, v56
	v_fma_f32 v55, -v55, v58, v57
	v_div_fmas_f32 v55, v55, v56, v58
	v_div_fixup_f32 v54, v55, v54, 2.0
	v_sub_f32_e32 v54, 1.0, v54
	v_add_f32_e32 v54, 1.0, v54
	v_mul_f32_e32 v50, v50, v54
	v_mul_f32_e32 v54, 0x3d372713, v51
	v_mul_f32_e32 v54, v51, v54
	v_fma_f32 v54, v51, v54, v51
	v_mul_f32_e32 v54, 0x3f4c422a, v54
	v_add_f32_e32 v54, v54, v54
	v_mul_f32_e32 v54, 0x3fb8aa3b, v54
	v_exp_f32_e32 v54, v54
	v_mul_f32_e32 v51, 0.5, v51
	v_add_f32_e32 v54, 1.0, v54
	v_div_scale_f32 v55, s[28:29], v54, v54, 2.0
	v_rcp_f32_e32 v56, v55
	s_nop 0
	v_fma_f32 v57, -v55, v56, 1.0
	v_fmac_f32_e32 v56, v57, v56
	v_div_scale_f32 v57, vcc, 2.0, v54, 2.0
	v_mul_f32_e32 v58, v57, v56
	v_fma_f32 v59, -v55, v58, v57
	v_fmac_f32_e32 v58, v59, v56
	v_fma_f32 v55, -v55, v58, v57
	v_div_fmas_f32 v55, v55, v56, v58
	v_div_fixup_f32 v54, v55, v54, 2.0
	v_sub_f32_e32 v54, 1.0, v54
	v_add_f32_e32 v54, 1.0, v54
	v_mul_f32_e32 v51, v51, v54
	v_mul_f32_e32 v54, 0x3d372713, v52
	v_mul_f32_e32 v54, v52, v54
	v_fma_f32 v54, v52, v54, v52
	v_mul_f32_e32 v54, 0x3f4c422a, v54
	v_add_f32_e32 v54, v54, v54
	v_mul_f32_e32 v54, 0x3fb8aa3b, v54
	v_exp_f32_e32 v54, v54
	v_mul_f32_e32 v52, 0.5, v52
	v_cvt_pk_bf16_f32 v198, v50, v51
	v_add_f32_e32 v54, 1.0, v54
	v_div_scale_f32 v55, s[28:29], v54, v54, 2.0
	v_rcp_f32_e32 v56, v55
	s_nop 0
	v_fma_f32 v57, -v55, v56, 1.0
	v_fmac_f32_e32 v56, v57, v56
	v_div_scale_f32 v57, vcc, 2.0, v54, 2.0
	v_mul_f32_e32 v58, v57, v56
	v_fma_f32 v59, -v55, v58, v57
	v_fmac_f32_e32 v58, v59, v56
	v_fma_f32 v55, -v55, v58, v57
	v_div_fmas_f32 v55, v55, v56, v58
	v_div_fixup_f32 v54, v55, v54, 2.0
	v_sub_f32_e32 v54, 1.0, v54
	v_add_f32_e32 v54, 1.0, v54
	v_mul_f32_e32 v52, v52, v54
	v_mul_f32_e32 v54, 0x3d372713, v53
	v_mul_f32_e32 v54, v53, v54
	v_fma_f32 v54, v53, v54, v53
	v_mul_f32_e32 v54, 0x3f4c422a, v54
	v_add_f32_e32 v54, v54, v54
	v_mul_f32_e32 v54, 0x3fb8aa3b, v54
	v_exp_f32_e32 v54, v54
	v_mul_f32_e32 v53, 0.5, v53
	v_add_f32_e32 v54, 1.0, v54
	v_div_scale_f32 v55, s[28:29], v54, v54, 2.0
	v_rcp_f32_e32 v56, v55
	s_nop 0
	v_fma_f32 v57, -v55, v56, 1.0
	v_fmac_f32_e32 v56, v57, v56
	v_div_scale_f32 v57, vcc, 2.0, v54, 2.0
	v_mul_f32_e32 v58, v57, v56
	v_fma_f32 v59, -v55, v58, v57
	v_fmac_f32_e32 v58, v59, v56
	v_fma_f32 v55, -v55, v58, v57
	v_div_fmas_f32 v55, v55, v56, v58
	v_div_fixup_f32 v54, v55, v54, 2.0
	v_sub_f32_e32 v54, 1.0, v54
	v_add_f32_e32 v54, 1.0, v54
	v_mul_f32_e32 v53, v53, v54
	v_cvt_pk_bf16_f32 v199, v52, v53
	s_nop 1
	v_permlane16_swap_b32_e32 v196, v198
	v_permlane16_swap_b32_e32 v197, v199
	v_lshl_add_u64 v[200:201], v[62:63], 0, v[202:203]
	global_store_dwordx4 v[200:201], v[196:199], off offset:256
	v_mov_b64_e32 v[50:51], v[176:177]
	v_mov_b64_e32 v[52:53], v[178:179]
	s_nop 0
	v_pk_add_f32 v[46:47], v[46:47], v[50:51]
	s_nop 0
	v_mul_f32_e32 v50, 0x3d372713, v46
	v_mul_f32_e32 v50, v46, v50
	v_fma_f32 v50, v46, v50, v46
	v_mul_f32_e32 v50, 0x3f4c422a, v50
	v_add_f32_e32 v50, v50, v50
	v_mul_f32_e32 v50, 0x3fb8aa3b, v50
	v_exp_f32_e32 v50, v50
	v_pk_add_f32 v[48:49], v[48:49], v[52:53]
	v_mul_f32_e32 v46, 0.5, v46
	v_add_f32_e32 v50, 1.0, v50
	v_div_scale_f32 v51, s[28:29], v50, v50, 2.0
	v_rcp_f32_e32 v52, v51
	s_nop 0
	v_fma_f32 v53, -v51, v52, 1.0
	v_fmac_f32_e32 v52, v53, v52
	v_div_scale_f32 v53, vcc, 2.0, v50, 2.0
	v_mul_f32_e32 v54, v53, v52
	v_fma_f32 v55, -v51, v54, v53
	v_fmac_f32_e32 v54, v55, v52
	v_fma_f32 v51, -v51, v54, v53
	v_div_fmas_f32 v51, v51, v52, v54
	v_div_fixup_f32 v50, v51, v50, 2.0
	v_sub_f32_e32 v50, 1.0, v50
	v_add_f32_e32 v50, 1.0, v50
	v_mul_f32_e32 v46, v46, v50
	v_mul_f32_e32 v50, 0x3d372713, v47
	v_mul_f32_e32 v50, v47, v50
	v_fma_f32 v50, v47, v50, v47
	v_mul_f32_e32 v50, 0x3f4c422a, v50
	v_add_f32_e32 v50, v50, v50
	v_mul_f32_e32 v50, 0x3fb8aa3b, v50
	v_exp_f32_e32 v50, v50
	v_mul_f32_e32 v47, 0.5, v47
	v_add_f32_e32 v50, 1.0, v50
	v_div_scale_f32 v51, s[28:29], v50, v50, 2.0
	v_rcp_f32_e32 v52, v51
	s_nop 0
	v_fma_f32 v53, -v51, v52, 1.0
	v_fmac_f32_e32 v52, v53, v52
	v_div_scale_f32 v53, vcc, 2.0, v50, 2.0
	v_mul_f32_e32 v54, v53, v52
	v_fma_f32 v55, -v51, v54, v53
	v_fmac_f32_e32 v54, v55, v52
	v_fma_f32 v51, -v51, v54, v53
	v_div_fmas_f32 v51, v51, v52, v54
	v_div_fixup_f32 v50, v51, v50, 2.0
	v_sub_f32_e32 v50, 1.0, v50
	v_add_f32_e32 v50, 1.0, v50
	v_mul_f32_e32 v47, v47, v50
	v_mul_f32_e32 v50, 0x3d372713, v48
	v_mul_f32_e32 v50, v48, v50
	v_fma_f32 v50, v48, v50, v48
	v_mul_f32_e32 v50, 0x3f4c422a, v50
	v_add_f32_e32 v50, v50, v50
	v_mul_f32_e32 v50, 0x3fb8aa3b, v50
	v_exp_f32_e32 v50, v50
	v_mul_f32_e32 v48, 0.5, v48
	v_add_f32_e32 v50, 1.0, v50
	v_div_scale_f32 v51, s[28:29], v50, v50, 2.0
	v_rcp_f32_e32 v52, v51
	s_nop 0
	v_fma_f32 v53, -v51, v52, 1.0
	v_fmac_f32_e32 v52, v53, v52
	v_div_scale_f32 v53, vcc, 2.0, v50, 2.0
	v_mul_f32_e32 v54, v53, v52
	v_fma_f32 v55, -v51, v54, v53
	v_fmac_f32_e32 v54, v55, v52
	v_fma_f32 v51, -v51, v54, v53
	v_div_fmas_f32 v51, v51, v52, v54
	v_div_fixup_f32 v50, v51, v50, 2.0
	v_sub_f32_e32 v50, 1.0, v50
	v_add_f32_e32 v50, 1.0, v50
	v_mul_f32_e32 v50, v48, v50
	v_mul_f32_e32 v48, 0x3d372713, v49
	v_mul_f32_e32 v48, v49, v48
	v_fma_f32 v48, v49, v48, v49
	v_mul_f32_e32 v48, 0x3f4c422a, v48
	v_add_f32_e32 v48, v48, v48
	v_mul_f32_e32 v48, 0x3fb8aa3b, v48
	v_exp_f32_e32 v48, v48
	v_mul_f32_e32 v49, 0.5, v49
	v_add_f32_e32 v48, 1.0, v48
	v_div_scale_f32 v51, s[28:29], v48, v48, 2.0
	v_rcp_f32_e32 v52, v51
	s_nop 0
	v_fma_f32 v53, -v51, v52, 1.0
	v_fmac_f32_e32 v52, v53, v52
	v_div_scale_f32 v53, vcc, 2.0, v48, 2.0
	v_mul_f32_e32 v54, v53, v52
	v_fma_f32 v55, -v51, v54, v53
	v_fmac_f32_e32 v54, v55, v52
	v_fma_f32 v51, -v51, v54, v53
	v_div_fmas_f32 v51, v51, v52, v54
	v_div_fixup_f32 v48, v51, v48, 2.0
	v_sub_f32_e32 v48, 1.0, v48
	v_add_f32_e32 v48, 1.0, v48
	v_mul_f32_e32 v49, v49, v48
	v_cvt_pk_bf16_f32 v192, v46, v47
	v_lshl_add_u64 v[46:47], s[26:27], 0, v[152:153]
	v_lshl_add_u64 v[46:47], v[46:47], 0, v[140:141]
	v_cvt_pk_bf16_f32 v193, v50, v49
	s_nop 0
	v_mov_b64_e32 v[48:49], v[180:181]
	v_mov_b64_e32 v[50:51], v[182:183]
	s_nop 0
	v_pk_add_f32 v[42:43], v[42:43], v[48:49]
	s_nop 0
	v_mul_f32_e32 v48, 0x3d372713, v42
	v_mul_f32_e32 v48, v42, v48
	v_fma_f32 v48, v42, v48, v42
	v_mul_f32_e32 v48, 0x3f4c422a, v48
	v_add_f32_e32 v48, v48, v48
	v_mul_f32_e32 v48, 0x3fb8aa3b, v48
	v_exp_f32_e32 v48, v48
	v_pk_add_f32 v[44:45], v[44:45], v[50:51]
	v_mul_f32_e32 v42, 0.5, v42
	v_add_f32_e32 v48, 1.0, v48
	v_div_scale_f32 v49, s[28:29], v48, v48, 2.0
	v_rcp_f32_e32 v50, v49
	s_nop 0
	v_fma_f32 v51, -v49, v50, 1.0
	v_fmac_f32_e32 v50, v51, v50
	v_div_scale_f32 v51, vcc, 2.0, v48, 2.0
	v_mul_f32_e32 v52, v51, v50
	v_fma_f32 v53, -v49, v52, v51
	v_fmac_f32_e32 v52, v53, v50
	v_fma_f32 v49, -v49, v52, v51
	v_div_fmas_f32 v49, v49, v50, v52
	v_div_fixup_f32 v48, v49, v48, 2.0
	v_sub_f32_e32 v48, 1.0, v48
	v_add_f32_e32 v48, 1.0, v48
	v_mul_f32_e32 v42, v42, v48
	v_mul_f32_e32 v48, 0x3d372713, v43
	v_mul_f32_e32 v48, v43, v48
	v_fma_f32 v48, v43, v48, v43
	v_mul_f32_e32 v48, 0x3f4c422a, v48
	v_add_f32_e32 v48, v48, v48
	v_mul_f32_e32 v48, 0x3fb8aa3b, v48
	v_exp_f32_e32 v48, v48
	v_mul_f32_e32 v43, 0.5, v43
	v_add_f32_e32 v48, 1.0, v48
	v_div_scale_f32 v49, s[28:29], v48, v48, 2.0
	v_rcp_f32_e32 v50, v49
	s_nop 0
	v_fma_f32 v51, -v49, v50, 1.0
	v_fmac_f32_e32 v50, v51, v50
	v_div_scale_f32 v51, vcc, 2.0, v48, 2.0
	v_mul_f32_e32 v52, v51, v50
	v_fma_f32 v53, -v49, v52, v51
	v_fmac_f32_e32 v52, v53, v50
	v_fma_f32 v49, -v49, v52, v51
	v_div_fmas_f32 v49, v49, v50, v52
	v_div_fixup_f32 v48, v49, v48, 2.0
	v_sub_f32_e32 v48, 1.0, v48
	v_add_f32_e32 v48, 1.0, v48
	v_mul_f32_e32 v43, v43, v48
	v_mul_f32_e32 v48, 0x3d372713, v44
	v_mul_f32_e32 v48, v44, v48
	v_fma_f32 v48, v44, v48, v44
	v_mul_f32_e32 v48, 0x3f4c422a, v48
	v_add_f32_e32 v48, v48, v48
	v_mul_f32_e32 v48, 0x3fb8aa3b, v48
	v_exp_f32_e32 v48, v48
	v_mul_f32_e32 v44, 0.5, v44
	v_cvt_pk_bf16_f32 v194, v42, v43
	v_add_f32_e32 v48, 1.0, v48
	v_div_scale_f32 v49, s[28:29], v48, v48, 2.0
	v_rcp_f32_e32 v50, v49
	s_nop 0
	v_fma_f32 v51, -v49, v50, 1.0
	v_fmac_f32_e32 v50, v51, v50
	v_div_scale_f32 v51, vcc, 2.0, v48, 2.0
	v_mul_f32_e32 v52, v51, v50
	v_fma_f32 v53, -v49, v52, v51
	v_fmac_f32_e32 v52, v53, v50
	v_fma_f32 v49, -v49, v52, v51
	v_div_fmas_f32 v49, v49, v50, v52
	v_div_fixup_f32 v48, v49, v48, 2.0
	v_sub_f32_e32 v48, 1.0, v48
	v_add_f32_e32 v48, 1.0, v48
	v_mul_f32_e32 v44, v44, v48
	v_mul_f32_e32 v48, 0x3d372713, v45
	v_mul_f32_e32 v48, v45, v48
	v_fma_f32 v48, v45, v48, v45
	v_mul_f32_e32 v48, 0x3f4c422a, v48
	v_add_f32_e32 v48, v48, v48
	v_mul_f32_e32 v48, 0x3fb8aa3b, v48
	v_exp_f32_e32 v48, v48
	v_mul_f32_e32 v45, 0.5, v45
	v_add_f32_e32 v48, 1.0, v48
	v_div_scale_f32 v49, s[28:29], v48, v48, 2.0
	v_rcp_f32_e32 v50, v49
	s_nop 0
	v_fma_f32 v51, -v49, v50, 1.0
	v_fmac_f32_e32 v50, v51, v50
	v_div_scale_f32 v51, vcc, 2.0, v48, 2.0
	v_mul_f32_e32 v52, v51, v50
	v_fma_f32 v53, -v49, v52, v51
	v_fmac_f32_e32 v52, v53, v50
	v_fma_f32 v49, -v49, v52, v51
	v_div_fmas_f32 v49, v49, v50, v52
	v_div_fixup_f32 v48, v49, v48, 2.0
	v_sub_f32_e32 v48, 1.0, v48
	v_add_f32_e32 v48, 1.0, v48
	v_mul_f32_e32 v45, v45, v48
	v_cvt_pk_bf16_f32 v195, v44, v45
	s_nop 1
	v_permlane16_swap_b32_e32 v192, v194
	v_permlane16_swap_b32_e32 v193, v195
	v_lshl_add_u64 v[200:201], v[46:47], 0, v[202:203]
	global_store_dwordx4 v[200:201], v[192:195], off
	v_mov_b64_e32 v[42:43], v[184:185]
	v_mov_b64_e32 v[44:45], v[186:187]
	s_nop 0
	v_pk_add_f32 v[38:39], v[38:39], v[42:43]
	s_nop 0
	v_mul_f32_e32 v42, 0x3d372713, v38
	v_mul_f32_e32 v42, v38, v42
	v_fma_f32 v42, v38, v42, v38
	v_mul_f32_e32 v42, 0x3f4c422a, v42
	v_add_f32_e32 v42, v42, v42
	v_mul_f32_e32 v42, 0x3fb8aa3b, v42
	v_exp_f32_e32 v42, v42
	v_pk_add_f32 v[40:41], v[40:41], v[44:45]
	v_mul_f32_e32 v38, 0.5, v38
	v_add_f32_e32 v42, 1.0, v42
	v_div_scale_f32 v43, s[28:29], v42, v42, 2.0
	v_rcp_f32_e32 v44, v43
	s_nop 0
	v_fma_f32 v45, -v43, v44, 1.0
	v_fmac_f32_e32 v44, v45, v44
	v_div_scale_f32 v45, vcc, 2.0, v42, 2.0
	v_mul_f32_e32 v48, v45, v44
	v_fma_f32 v49, -v43, v48, v45
	v_fmac_f32_e32 v48, v49, v44
	v_fma_f32 v43, -v43, v48, v45
	v_div_fmas_f32 v43, v43, v44, v48
	v_div_fixup_f32 v42, v43, v42, 2.0
	v_sub_f32_e32 v42, 1.0, v42
	v_add_f32_e32 v42, 1.0, v42
	v_mul_f32_e32 v38, v38, v42
	v_mul_f32_e32 v42, 0x3d372713, v39
	v_mul_f32_e32 v42, v39, v42
	v_fma_f32 v42, v39, v42, v39
	v_mul_f32_e32 v42, 0x3f4c422a, v42
	v_add_f32_e32 v42, v42, v42
	v_mul_f32_e32 v42, 0x3fb8aa3b, v42
	v_exp_f32_e32 v42, v42
	v_mul_f32_e32 v39, 0.5, v39
	v_add_f32_e32 v42, 1.0, v42
	v_div_scale_f32 v43, s[28:29], v42, v42, 2.0
	v_rcp_f32_e32 v44, v43
	s_nop 0
	v_fma_f32 v45, -v43, v44, 1.0
	v_fmac_f32_e32 v44, v45, v44
	v_div_scale_f32 v45, vcc, 2.0, v42, 2.0
	v_mul_f32_e32 v48, v45, v44
	v_fma_f32 v49, -v43, v48, v45
	v_fmac_f32_e32 v48, v49, v44
	v_fma_f32 v43, -v43, v48, v45
	v_div_fmas_f32 v43, v43, v44, v48
	v_div_fixup_f32 v42, v43, v42, 2.0
	v_sub_f32_e32 v42, 1.0, v42
	v_add_f32_e32 v42, 1.0, v42
	v_mul_f32_e32 v39, v39, v42
	v_mul_f32_e32 v42, 0x3d372713, v40
	v_mul_f32_e32 v42, v40, v42
	v_fma_f32 v42, v40, v42, v40
	v_mul_f32_e32 v42, 0x3f4c422a, v42
	v_add_f32_e32 v42, v42, v42
	v_mul_f32_e32 v42, 0x3fb8aa3b, v42
	v_exp_f32_e32 v42, v42
	v_mul_f32_e32 v40, 0.5, v40
	v_cvt_pk_bf16_f32 v196, v38, v39
	v_add_f32_e32 v42, 1.0, v42
	v_div_scale_f32 v43, s[28:29], v42, v42, 2.0
	v_rcp_f32_e32 v44, v43
	s_nop 0
	v_fma_f32 v45, -v43, v44, 1.0
	v_fmac_f32_e32 v44, v45, v44
	v_div_scale_f32 v45, vcc, 2.0, v42, 2.0
	v_mul_f32_e32 v48, v45, v44
	v_fma_f32 v49, -v43, v48, v45
	v_fmac_f32_e32 v48, v49, v44
	v_fma_f32 v43, -v43, v48, v45
	v_div_fmas_f32 v43, v43, v44, v48
	v_div_fixup_f32 v42, v43, v42, 2.0
	v_sub_f32_e32 v42, 1.0, v42
	v_add_f32_e32 v42, 1.0, v42
	v_mul_f32_e32 v40, v40, v42
	v_mul_f32_e32 v42, 0x3d372713, v41
	v_mul_f32_e32 v42, v41, v42
	v_fma_f32 v42, v41, v42, v41
	v_mul_f32_e32 v42, 0x3f4c422a, v42
	v_add_f32_e32 v42, v42, v42
	v_mul_f32_e32 v42, 0x3fb8aa3b, v42
	v_exp_f32_e32 v42, v42
	v_mul_f32_e32 v41, 0.5, v41
	v_add_f32_e32 v42, 1.0, v42
	v_div_scale_f32 v43, s[28:29], v42, v42, 2.0
	v_rcp_f32_e32 v44, v43
	s_nop 0
	v_fma_f32 v45, -v43, v44, 1.0
	v_fmac_f32_e32 v44, v45, v44
	v_div_scale_f32 v45, vcc, 2.0, v42, 2.0
	v_mul_f32_e32 v48, v45, v44
	v_fma_f32 v49, -v43, v48, v45
	v_fmac_f32_e32 v48, v49, v44
	v_fma_f32 v43, -v43, v48, v45
	v_div_fmas_f32 v43, v43, v44, v48
	v_div_fixup_f32 v42, v43, v42, 2.0
	v_sub_f32_e32 v42, 1.0, v42
	v_add_f32_e32 v42, 1.0, v42
	v_mul_f32_e32 v41, v41, v42
	v_cvt_pk_bf16_f32 v197, v40, v41
	s_nop 0
	v_mov_b64_e32 v[38:39], v[188:189]
	v_mov_b64_e32 v[40:41], v[190:191]
	s_nop 0
	v_pk_add_f32 v[34:35], v[34:35], v[38:39]
	s_nop 0
	v_mul_f32_e32 v38, 0x3d372713, v34
	v_mul_f32_e32 v38, v34, v38
	v_fma_f32 v38, v34, v38, v34
	v_mul_f32_e32 v38, 0x3f4c422a, v38
	v_add_f32_e32 v38, v38, v38
	v_mul_f32_e32 v38, 0x3fb8aa3b, v38
	v_exp_f32_e32 v38, v38
	v_pk_add_f32 v[36:37], v[36:37], v[40:41]
	v_mul_f32_e32 v34, 0.5, v34
	v_add_f32_e32 v38, 1.0, v38
	v_div_scale_f32 v39, s[28:29], v38, v38, 2.0
	v_rcp_f32_e32 v40, v39
	s_nop 0
	v_fma_f32 v41, -v39, v40, 1.0
	v_fmac_f32_e32 v40, v41, v40
	v_div_scale_f32 v41, vcc, 2.0, v38, 2.0
	v_mul_f32_e32 v42, v41, v40
	v_fma_f32 v43, -v39, v42, v41
	v_fmac_f32_e32 v42, v43, v40
	v_fma_f32 v39, -v39, v42, v41
	v_div_fmas_f32 v39, v39, v40, v42
	v_div_fixup_f32 v38, v39, v38, 2.0
	v_sub_f32_e32 v38, 1.0, v38
	v_add_f32_e32 v38, 1.0, v38
	v_mul_f32_e32 v34, v34, v38
	v_mul_f32_e32 v38, 0x3d372713, v35
	v_mul_f32_e32 v38, v35, v38
	v_fma_f32 v38, v35, v38, v35
	v_mul_f32_e32 v38, 0x3f4c422a, v38
	v_add_f32_e32 v38, v38, v38
	v_mul_f32_e32 v38, 0x3fb8aa3b, v38
	v_exp_f32_e32 v38, v38
	v_mul_f32_e32 v35, 0.5, v35
	v_add_f32_e32 v38, 1.0, v38
	v_div_scale_f32 v39, s[28:29], v38, v38, 2.0
	v_rcp_f32_e32 v40, v39
	s_nop 0
	v_fma_f32 v41, -v39, v40, 1.0
	v_fmac_f32_e32 v40, v41, v40
	v_div_scale_f32 v41, vcc, 2.0, v38, 2.0
	v_mul_f32_e32 v42, v41, v40
	v_fma_f32 v43, -v39, v42, v41
	v_fmac_f32_e32 v42, v43, v40
	v_fma_f32 v39, -v39, v42, v41
	v_div_fmas_f32 v39, v39, v40, v42
	v_div_fixup_f32 v38, v39, v38, 2.0
	v_sub_f32_e32 v38, 1.0, v38
	v_add_f32_e32 v38, 1.0, v38
	v_mul_f32_e32 v35, v35, v38
	v_mul_f32_e32 v38, 0x3d372713, v36
	v_mul_f32_e32 v38, v36, v38
	v_fma_f32 v38, v36, v38, v36
	v_mul_f32_e32 v38, 0x3f4c422a, v38
	v_add_f32_e32 v38, v38, v38
	v_mul_f32_e32 v38, 0x3fb8aa3b, v38
	v_exp_f32_e32 v38, v38
	v_mul_f32_e32 v36, 0.5, v36
	v_cvt_pk_bf16_f32 v198, v34, v35
	v_add_f32_e32 v38, 1.0, v38
	v_div_scale_f32 v39, s[28:29], v38, v38, 2.0
	v_rcp_f32_e32 v40, v39
	s_nop 0
	v_fma_f32 v41, -v39, v40, 1.0
	v_fmac_f32_e32 v40, v41, v40
	v_div_scale_f32 v41, vcc, 2.0, v38, 2.0
	v_mul_f32_e32 v42, v41, v40
	v_fma_f32 v43, -v39, v42, v41
	v_fmac_f32_e32 v42, v43, v40
	v_fma_f32 v39, -v39, v42, v41
	v_div_fmas_f32 v39, v39, v40, v42
	v_div_fixup_f32 v38, v39, v38, 2.0
	v_sub_f32_e32 v38, 1.0, v38
	v_add_f32_e32 v38, 1.0, v38
	v_mul_f32_e32 v36, v36, v38
	v_mul_f32_e32 v38, 0x3d372713, v37
	v_mul_f32_e32 v38, v37, v38
	v_fma_f32 v38, v37, v38, v37
	v_mul_f32_e32 v38, 0x3f4c422a, v38
	v_add_f32_e32 v38, v38, v38
	v_mul_f32_e32 v38, 0x3fb8aa3b, v38
	v_exp_f32_e32 v38, v38
	v_mul_f32_e32 v37, 0.5, v37
	v_add_f32_e32 v38, 1.0, v38
	v_div_scale_f32 v39, s[28:29], v38, v38, 2.0
	v_rcp_f32_e32 v40, v39
	s_nop 0
	v_fma_f32 v41, -v39, v40, 1.0
	v_fmac_f32_e32 v40, v41, v40
	v_div_scale_f32 v41, vcc, 2.0, v38, 2.0
	v_mul_f32_e32 v42, v41, v40
	v_fma_f32 v43, -v39, v42, v41
	v_fmac_f32_e32 v42, v43, v40
	v_fma_f32 v39, -v39, v42, v41
	v_div_fmas_f32 v39, v39, v40, v42
	v_div_fixup_f32 v38, v39, v38, 2.0
	v_sub_f32_e32 v38, 1.0, v38
	v_add_f32_e32 v38, 1.0, v38
	v_mul_f32_e32 v37, v37, v38
	v_cvt_pk_bf16_f32 v199, v36, v37
	s_nop 1
	v_permlane16_swap_b32_e32 v196, v198
	v_permlane16_swap_b32_e32 v197, v199
	v_lshl_add_u64 v[200:201], v[46:47], 0, v[202:203]
	global_store_dwordx4 v[200:201], v[196:199], off offset:256
	v_mov_b64_e32 v[34:35], v[176:177]
	v_mov_b64_e32 v[36:37], v[178:179]
	s_nop 0
	v_pk_add_f32 v[30:31], v[30:31], v[34:35]
	s_nop 0
	v_mul_f32_e32 v34, 0x3d372713, v30
	v_mul_f32_e32 v34, v30, v34
	v_fma_f32 v34, v30, v34, v30
	v_mul_f32_e32 v34, 0x3f4c422a, v34
	v_add_f32_e32 v34, v34, v34
	v_mul_f32_e32 v34, 0x3fb8aa3b, v34
	v_exp_f32_e32 v34, v34
	v_pk_add_f32 v[32:33], v[32:33], v[36:37]
	v_mul_f32_e32 v30, 0.5, v30
	v_add_f32_e32 v34, 1.0, v34
	v_div_scale_f32 v35, s[28:29], v34, v34, 2.0
	v_rcp_f32_e32 v36, v35
	s_nop 0
	v_fma_f32 v37, -v35, v36, 1.0
	v_fmac_f32_e32 v36, v37, v36
	v_div_scale_f32 v37, vcc, 2.0, v34, 2.0
	v_mul_f32_e32 v38, v37, v36
	v_fma_f32 v39, -v35, v38, v37
	v_fmac_f32_e32 v38, v39, v36
	v_fma_f32 v35, -v35, v38, v37
	v_div_fmas_f32 v35, v35, v36, v38
	v_div_fixup_f32 v34, v35, v34, 2.0
	v_sub_f32_e32 v34, 1.0, v34
	v_add_f32_e32 v34, 1.0, v34
	v_mul_f32_e32 v30, v30, v34
	v_mul_f32_e32 v34, 0x3d372713, v31
	v_mul_f32_e32 v34, v31, v34
	v_fma_f32 v34, v31, v34, v31
	v_mul_f32_e32 v34, 0x3f4c422a, v34
	v_add_f32_e32 v34, v34, v34
	v_mul_f32_e32 v34, 0x3fb8aa3b, v34
	v_exp_f32_e32 v34, v34
	v_mul_f32_e32 v31, 0.5, v31
	v_add_f32_e32 v34, 1.0, v34
	v_div_scale_f32 v35, s[28:29], v34, v34, 2.0
	v_rcp_f32_e32 v36, v35
	s_nop 0
	v_fma_f32 v37, -v35, v36, 1.0
	v_fmac_f32_e32 v36, v37, v36
	v_div_scale_f32 v37, vcc, 2.0, v34, 2.0
	v_mul_f32_e32 v38, v37, v36
	v_fma_f32 v39, -v35, v38, v37
	v_fmac_f32_e32 v38, v39, v36
	v_fma_f32 v35, -v35, v38, v37
	v_div_fmas_f32 v35, v35, v36, v38
	v_div_fixup_f32 v34, v35, v34, 2.0
	v_sub_f32_e32 v34, 1.0, v34
	v_add_f32_e32 v34, 1.0, v34
	v_mul_f32_e32 v31, v31, v34
	v_mul_f32_e32 v34, 0x3d372713, v32
	v_mul_f32_e32 v34, v32, v34
	v_fma_f32 v34, v32, v34, v32
	v_mul_f32_e32 v34, 0x3f4c422a, v34
	v_add_f32_e32 v34, v34, v34
	v_mul_f32_e32 v34, 0x3fb8aa3b, v34
	v_exp_f32_e32 v34, v34
	v_mul_f32_e32 v32, 0.5, v32
	v_add_f32_e32 v34, 1.0, v34
	v_div_scale_f32 v35, s[28:29], v34, v34, 2.0
	v_rcp_f32_e32 v36, v35
	s_nop 0
	v_fma_f32 v37, -v35, v36, 1.0
	v_fmac_f32_e32 v36, v37, v36
	v_div_scale_f32 v37, vcc, 2.0, v34, 2.0
	v_mul_f32_e32 v38, v37, v36
	v_fma_f32 v39, -v35, v38, v37
	v_fmac_f32_e32 v38, v39, v36
	v_fma_f32 v35, -v35, v38, v37
	v_div_fmas_f32 v35, v35, v36, v38
	v_div_fixup_f32 v34, v35, v34, 2.0
	v_sub_f32_e32 v34, 1.0, v34
	v_add_f32_e32 v34, 1.0, v34
	v_mul_f32_e32 v34, v32, v34
	v_mul_f32_e32 v32, 0x3d372713, v33
	v_mul_f32_e32 v32, v33, v32
	v_fma_f32 v32, v33, v32, v33
	v_mul_f32_e32 v32, 0x3f4c422a, v32
	v_add_f32_e32 v32, v32, v32
	v_mul_f32_e32 v32, 0x3fb8aa3b, v32
	v_exp_f32_e32 v32, v32
	v_mul_f32_e32 v33, 0.5, v33
	v_add_f32_e32 v32, 1.0, v32
	v_div_scale_f32 v35, s[28:29], v32, v32, 2.0
	v_rcp_f32_e32 v36, v35
	s_nop 0
	v_fma_f32 v37, -v35, v36, 1.0
	v_fmac_f32_e32 v36, v37, v36
	v_div_scale_f32 v37, vcc, 2.0, v32, 2.0
	v_mul_f32_e32 v38, v37, v36
	v_fma_f32 v39, -v35, v38, v37
	v_fmac_f32_e32 v38, v39, v36
	v_fma_f32 v35, -v35, v38, v37
	v_div_fmas_f32 v35, v35, v36, v38
	v_div_fixup_f32 v32, v35, v32, 2.0
	v_sub_f32_e32 v32, 1.0, v32
	v_add_f32_e32 v32, 1.0, v32
	v_mul_f32_e32 v33, v33, v32
	v_cvt_pk_bf16_f32 v192, v30, v31
	v_lshl_add_u64 v[30:31], s[26:27], 0, v[154:155]
	v_lshl_add_u64 v[30:31], v[30:31], 0, v[140:141]
	v_cvt_pk_bf16_f32 v193, v34, v33
	s_nop 0
	v_mov_b64_e32 v[32:33], v[180:181]
	v_mov_b64_e32 v[34:35], v[182:183]
	s_nop 0
	v_pk_add_f32 v[26:27], v[26:27], v[32:33]
	s_nop 0
	v_mul_f32_e32 v32, 0x3d372713, v26
	v_mul_f32_e32 v32, v26, v32
	v_fma_f32 v32, v26, v32, v26
	v_mul_f32_e32 v32, 0x3f4c422a, v32
	v_add_f32_e32 v32, v32, v32
	v_mul_f32_e32 v32, 0x3fb8aa3b, v32
	v_exp_f32_e32 v32, v32
	v_pk_add_f32 v[28:29], v[28:29], v[34:35]
	v_mul_f32_e32 v26, 0.5, v26
	v_add_f32_e32 v32, 1.0, v32
	v_div_scale_f32 v33, s[28:29], v32, v32, 2.0
	v_rcp_f32_e32 v34, v33
	s_nop 0
	v_fma_f32 v35, -v33, v34, 1.0
	v_fmac_f32_e32 v34, v35, v34
	v_div_scale_f32 v35, vcc, 2.0, v32, 2.0
	v_mul_f32_e32 v36, v35, v34
	v_fma_f32 v37, -v33, v36, v35
	v_fmac_f32_e32 v36, v37, v34
	v_fma_f32 v33, -v33, v36, v35
	v_div_fmas_f32 v33, v33, v34, v36
	v_div_fixup_f32 v32, v33, v32, 2.0
	v_sub_f32_e32 v32, 1.0, v32
	v_add_f32_e32 v32, 1.0, v32
	v_mul_f32_e32 v26, v26, v32
	v_mul_f32_e32 v32, 0x3d372713, v27
	v_mul_f32_e32 v32, v27, v32
	v_fma_f32 v32, v27, v32, v27
	v_mul_f32_e32 v32, 0x3f4c422a, v32
	v_add_f32_e32 v32, v32, v32
	v_mul_f32_e32 v32, 0x3fb8aa3b, v32
	v_exp_f32_e32 v32, v32
	v_mul_f32_e32 v27, 0.5, v27
	v_add_f32_e32 v32, 1.0, v32
	v_div_scale_f32 v33, s[28:29], v32, v32, 2.0
	v_rcp_f32_e32 v34, v33
	s_nop 0
	v_fma_f32 v35, -v33, v34, 1.0
	v_fmac_f32_e32 v34, v35, v34
	v_div_scale_f32 v35, vcc, 2.0, v32, 2.0
	v_mul_f32_e32 v36, v35, v34
	v_fma_f32 v37, -v33, v36, v35
	v_fmac_f32_e32 v36, v37, v34
	v_fma_f32 v33, -v33, v36, v35
	v_div_fmas_f32 v33, v33, v34, v36
	v_div_fixup_f32 v32, v33, v32, 2.0
	v_sub_f32_e32 v32, 1.0, v32
	v_add_f32_e32 v32, 1.0, v32
	v_mul_f32_e32 v27, v27, v32
	v_mul_f32_e32 v32, 0x3d372713, v28
	v_mul_f32_e32 v32, v28, v32
	v_fma_f32 v32, v28, v32, v28
	v_mul_f32_e32 v32, 0x3f4c422a, v32
	v_add_f32_e32 v32, v32, v32
	v_mul_f32_e32 v32, 0x3fb8aa3b, v32
	v_exp_f32_e32 v32, v32
	v_mul_f32_e32 v28, 0.5, v28
	v_cvt_pk_bf16_f32 v194, v26, v27
	v_add_f32_e32 v32, 1.0, v32
	v_div_scale_f32 v33, s[28:29], v32, v32, 2.0
	v_rcp_f32_e32 v34, v33
	s_nop 0
	v_fma_f32 v35, -v33, v34, 1.0
	v_fmac_f32_e32 v34, v35, v34
	v_div_scale_f32 v35, vcc, 2.0, v32, 2.0
	v_mul_f32_e32 v36, v35, v34
	v_fma_f32 v37, -v33, v36, v35
	v_fmac_f32_e32 v36, v37, v34
	v_fma_f32 v33, -v33, v36, v35
	v_div_fmas_f32 v33, v33, v34, v36
	v_div_fixup_f32 v32, v33, v32, 2.0
	v_sub_f32_e32 v32, 1.0, v32
	v_add_f32_e32 v32, 1.0, v32
	v_mul_f32_e32 v28, v28, v32
	v_mul_f32_e32 v32, 0x3d372713, v29
	v_mul_f32_e32 v32, v29, v32
	v_fma_f32 v32, v29, v32, v29
	v_mul_f32_e32 v32, 0x3f4c422a, v32
	v_add_f32_e32 v32, v32, v32
	v_mul_f32_e32 v32, 0x3fb8aa3b, v32
	v_exp_f32_e32 v32, v32
	v_mul_f32_e32 v29, 0.5, v29
	v_add_f32_e32 v32, 1.0, v32
	v_div_scale_f32 v33, s[28:29], v32, v32, 2.0
	v_rcp_f32_e32 v34, v33
	s_nop 0
	v_fma_f32 v35, -v33, v34, 1.0
	v_fmac_f32_e32 v34, v35, v34
	v_div_scale_f32 v35, vcc, 2.0, v32, 2.0
	v_mul_f32_e32 v36, v35, v34
	v_fma_f32 v37, -v33, v36, v35
	v_fmac_f32_e32 v36, v37, v34
	v_fma_f32 v33, -v33, v36, v35
	v_div_fmas_f32 v33, v33, v34, v36
	v_div_fixup_f32 v32, v33, v32, 2.0
	v_sub_f32_e32 v32, 1.0, v32
	v_add_f32_e32 v32, 1.0, v32
	v_mul_f32_e32 v29, v29, v32
	v_cvt_pk_bf16_f32 v195, v28, v29
	s_nop 1
	v_permlane16_swap_b32_e32 v192, v194
	v_permlane16_swap_b32_e32 v193, v195
	v_lshl_add_u64 v[200:201], v[30:31], 0, v[202:203]
	global_store_dwordx4 v[200:201], v[192:195], off
	v_mov_b64_e32 v[26:27], v[184:185]
	v_mov_b64_e32 v[28:29], v[186:187]
	s_nop 0
	v_pk_add_f32 v[22:23], v[22:23], v[26:27]
	s_nop 0
	v_mul_f32_e32 v26, 0x3d372713, v22
	v_mul_f32_e32 v26, v22, v26
	v_fma_f32 v26, v22, v26, v22
	v_mul_f32_e32 v26, 0x3f4c422a, v26
	v_add_f32_e32 v26, v26, v26
	v_mul_f32_e32 v26, 0x3fb8aa3b, v26
	v_exp_f32_e32 v26, v26
	v_pk_add_f32 v[24:25], v[24:25], v[28:29]
	v_mul_f32_e32 v22, 0.5, v22
	v_add_f32_e32 v26, 1.0, v26
	v_div_scale_f32 v27, s[28:29], v26, v26, 2.0
	v_rcp_f32_e32 v28, v27
	s_nop 0
	v_fma_f32 v29, -v27, v28, 1.0
	v_fmac_f32_e32 v28, v29, v28
	v_div_scale_f32 v29, vcc, 2.0, v26, 2.0
	v_mul_f32_e32 v32, v29, v28
	v_fma_f32 v33, -v27, v32, v29
	v_fmac_f32_e32 v32, v33, v28
	v_fma_f32 v27, -v27, v32, v29
	v_div_fmas_f32 v27, v27, v28, v32
	v_div_fixup_f32 v26, v27, v26, 2.0
	v_sub_f32_e32 v26, 1.0, v26
	v_add_f32_e32 v26, 1.0, v26
	v_mul_f32_e32 v22, v22, v26
	v_mul_f32_e32 v26, 0x3d372713, v23
	v_mul_f32_e32 v26, v23, v26
	v_fma_f32 v26, v23, v26, v23
	v_mul_f32_e32 v26, 0x3f4c422a, v26
	v_add_f32_e32 v26, v26, v26
	v_mul_f32_e32 v26, 0x3fb8aa3b, v26
	v_exp_f32_e32 v26, v26
	v_mul_f32_e32 v23, 0.5, v23
	v_add_f32_e32 v26, 1.0, v26
	v_div_scale_f32 v27, s[28:29], v26, v26, 2.0
	v_rcp_f32_e32 v28, v27
	s_nop 0
	v_fma_f32 v29, -v27, v28, 1.0
	v_fmac_f32_e32 v28, v29, v28
	v_div_scale_f32 v29, vcc, 2.0, v26, 2.0
	v_mul_f32_e32 v32, v29, v28
	v_fma_f32 v33, -v27, v32, v29
	v_fmac_f32_e32 v32, v33, v28
	v_fma_f32 v27, -v27, v32, v29
	v_div_fmas_f32 v27, v27, v28, v32
	v_div_fixup_f32 v26, v27, v26, 2.0
	v_sub_f32_e32 v26, 1.0, v26
	v_add_f32_e32 v26, 1.0, v26
	v_mul_f32_e32 v23, v23, v26
	v_mul_f32_e32 v26, 0x3d372713, v24
	v_mul_f32_e32 v26, v24, v26
	v_fma_f32 v26, v24, v26, v24
	v_mul_f32_e32 v26, 0x3f4c422a, v26
	v_add_f32_e32 v26, v26, v26
	v_mul_f32_e32 v26, 0x3fb8aa3b, v26
	v_exp_f32_e32 v26, v26
	v_mul_f32_e32 v24, 0.5, v24
	v_cvt_pk_bf16_f32 v196, v22, v23
	v_add_f32_e32 v26, 1.0, v26
	v_div_scale_f32 v27, s[28:29], v26, v26, 2.0
	v_rcp_f32_e32 v28, v27
	s_nop 0
	v_fma_f32 v29, -v27, v28, 1.0
	v_fmac_f32_e32 v28, v29, v28
	v_div_scale_f32 v29, vcc, 2.0, v26, 2.0
	v_mul_f32_e32 v32, v29, v28
	v_fma_f32 v33, -v27, v32, v29
	v_fmac_f32_e32 v32, v33, v28
	v_fma_f32 v27, -v27, v32, v29
	v_div_fmas_f32 v27, v27, v28, v32
	v_div_fixup_f32 v26, v27, v26, 2.0
	v_sub_f32_e32 v26, 1.0, v26
	v_add_f32_e32 v26, 1.0, v26
	v_mul_f32_e32 v24, v24, v26
	v_mul_f32_e32 v26, 0x3d372713, v25
	v_mul_f32_e32 v26, v25, v26
	v_fma_f32 v26, v25, v26, v25
	v_mul_f32_e32 v26, 0x3f4c422a, v26
	v_add_f32_e32 v26, v26, v26
	v_mul_f32_e32 v26, 0x3fb8aa3b, v26
	v_exp_f32_e32 v26, v26
	v_mul_f32_e32 v25, 0.5, v25
	v_add_f32_e32 v26, 1.0, v26
	v_div_scale_f32 v27, s[28:29], v26, v26, 2.0
	v_rcp_f32_e32 v28, v27
	s_nop 0
	v_fma_f32 v29, -v27, v28, 1.0
	v_fmac_f32_e32 v28, v29, v28
	v_div_scale_f32 v29, vcc, 2.0, v26, 2.0
	v_mul_f32_e32 v32, v29, v28
	v_fma_f32 v33, -v27, v32, v29
	v_fmac_f32_e32 v32, v33, v28
	v_fma_f32 v27, -v27, v32, v29
	v_div_fmas_f32 v27, v27, v28, v32
	v_div_fixup_f32 v26, v27, v26, 2.0
	v_sub_f32_e32 v26, 1.0, v26
	v_add_f32_e32 v26, 1.0, v26
	v_mul_f32_e32 v25, v25, v26
	v_cvt_pk_bf16_f32 v197, v24, v25
	s_nop 0
	v_mov_b64_e32 v[22:23], v[188:189]
	v_mov_b64_e32 v[24:25], v[190:191]
	s_nop 0
	v_pk_add_f32 v[18:19], v[18:19], v[22:23]
	s_nop 0
	v_mul_f32_e32 v22, 0x3d372713, v18
	v_mul_f32_e32 v22, v18, v22
	v_fma_f32 v22, v18, v22, v18
	v_mul_f32_e32 v22, 0x3f4c422a, v22
	v_add_f32_e32 v22, v22, v22
	v_mul_f32_e32 v22, 0x3fb8aa3b, v22
	v_exp_f32_e32 v22, v22
	v_pk_add_f32 v[20:21], v[20:21], v[24:25]
	v_mul_f32_e32 v18, 0.5, v18
	v_add_f32_e32 v22, 1.0, v22
	v_div_scale_f32 v23, s[28:29], v22, v22, 2.0
	v_rcp_f32_e32 v24, v23
	s_nop 0
	v_fma_f32 v25, -v23, v24, 1.0
	v_fmac_f32_e32 v24, v25, v24
	v_div_scale_f32 v25, vcc, 2.0, v22, 2.0
	v_mul_f32_e32 v26, v25, v24
	v_fma_f32 v27, -v23, v26, v25
	v_fmac_f32_e32 v26, v27, v24
	v_fma_f32 v23, -v23, v26, v25
	v_div_fmas_f32 v23, v23, v24, v26
	v_div_fixup_f32 v22, v23, v22, 2.0
	v_sub_f32_e32 v22, 1.0, v22
	v_add_f32_e32 v22, 1.0, v22
	v_mul_f32_e32 v18, v18, v22
	v_mul_f32_e32 v22, 0x3d372713, v19
	v_mul_f32_e32 v22, v19, v22
	v_fma_f32 v22, v19, v22, v19
	v_mul_f32_e32 v22, 0x3f4c422a, v22
	v_add_f32_e32 v22, v22, v22
	v_mul_f32_e32 v22, 0x3fb8aa3b, v22
	v_exp_f32_e32 v22, v22
	v_mul_f32_e32 v19, 0.5, v19
	v_add_f32_e32 v22, 1.0, v22
	v_div_scale_f32 v23, s[28:29], v22, v22, 2.0
	v_rcp_f32_e32 v24, v23
	s_nop 0
	v_fma_f32 v25, -v23, v24, 1.0
	v_fmac_f32_e32 v24, v25, v24
	v_div_scale_f32 v25, vcc, 2.0, v22, 2.0
	v_mul_f32_e32 v26, v25, v24
	v_fma_f32 v27, -v23, v26, v25
	v_fmac_f32_e32 v26, v27, v24
	v_fma_f32 v23, -v23, v26, v25
	v_div_fmas_f32 v23, v23, v24, v26
	v_div_fixup_f32 v22, v23, v22, 2.0
	v_sub_f32_e32 v22, 1.0, v22
	v_add_f32_e32 v22, 1.0, v22
	v_mul_f32_e32 v19, v19, v22
	v_mul_f32_e32 v22, 0x3d372713, v20
	v_mul_f32_e32 v22, v20, v22
	v_fma_f32 v22, v20, v22, v20
	v_mul_f32_e32 v22, 0x3f4c422a, v22
	v_add_f32_e32 v22, v22, v22
	v_mul_f32_e32 v22, 0x3fb8aa3b, v22
	v_exp_f32_e32 v22, v22
	v_mul_f32_e32 v20, 0.5, v20
	v_cvt_pk_bf16_f32 v198, v18, v19
	v_add_f32_e32 v22, 1.0, v22
	v_div_scale_f32 v23, s[28:29], v22, v22, 2.0
	v_rcp_f32_e32 v24, v23
	s_nop 0
	v_fma_f32 v25, -v23, v24, 1.0
	v_fmac_f32_e32 v24, v25, v24
	v_div_scale_f32 v25, vcc, 2.0, v22, 2.0
	v_mul_f32_e32 v26, v25, v24
	v_fma_f32 v27, -v23, v26, v25
	v_fmac_f32_e32 v26, v27, v24
	v_fma_f32 v23, -v23, v26, v25
	v_div_fmas_f32 v23, v23, v24, v26
	v_div_fixup_f32 v22, v23, v22, 2.0
	v_sub_f32_e32 v22, 1.0, v22
	v_add_f32_e32 v22, 1.0, v22
	v_mul_f32_e32 v20, v20, v22
	v_mul_f32_e32 v22, 0x3d372713, v21
	v_mul_f32_e32 v22, v21, v22
	v_fma_f32 v22, v21, v22, v21
	v_mul_f32_e32 v22, 0x3f4c422a, v22
	v_add_f32_e32 v22, v22, v22
	v_mul_f32_e32 v22, 0x3fb8aa3b, v22
	v_exp_f32_e32 v22, v22
	v_mul_f32_e32 v21, 0.5, v21
	v_add_f32_e32 v22, 1.0, v22
	v_div_scale_f32 v23, s[28:29], v22, v22, 2.0
	v_rcp_f32_e32 v24, v23
	s_nop 0
	v_fma_f32 v25, -v23, v24, 1.0
	v_fmac_f32_e32 v24, v25, v24
	v_div_scale_f32 v25, vcc, 2.0, v22, 2.0
	v_mul_f32_e32 v26, v25, v24
	v_fma_f32 v27, -v23, v26, v25
	v_fmac_f32_e32 v26, v27, v24
	v_fma_f32 v23, -v23, v26, v25
	v_div_fmas_f32 v23, v23, v24, v26
	v_div_fixup_f32 v22, v23, v22, 2.0
	v_sub_f32_e32 v22, 1.0, v22
	v_add_f32_e32 v22, 1.0, v22
	v_mul_f32_e32 v21, v21, v22
	v_cvt_pk_bf16_f32 v199, v20, v21
	s_nop 1
	v_permlane16_swap_b32_e32 v196, v198
	v_permlane16_swap_b32_e32 v197, v199
	v_lshl_add_u64 v[200:201], v[30:31], 0, v[202:203]
	global_store_dwordx4 v[200:201], v[196:199], off offset:256
	v_mov_b64_e32 v[18:19], v[176:177]
	v_mov_b64_e32 v[20:21], v[178:179]
	s_nop 0
	v_pk_add_f32 v[14:15], v[14:15], v[18:19]
	s_nop 0
	v_mul_f32_e32 v18, 0x3d372713, v14
	v_mul_f32_e32 v18, v14, v18
	v_fma_f32 v18, v14, v18, v14
	v_mul_f32_e32 v18, 0x3f4c422a, v18
	v_add_f32_e32 v18, v18, v18
	v_mul_f32_e32 v18, 0x3fb8aa3b, v18
	v_exp_f32_e32 v18, v18
	v_pk_add_f32 v[16:17], v[16:17], v[20:21]
	v_mul_f32_e32 v14, 0.5, v14
	v_add_f32_e32 v18, 1.0, v18
	v_div_scale_f32 v19, s[28:29], v18, v18, 2.0
	v_rcp_f32_e32 v20, v19
	s_nop 0
	v_fma_f32 v21, -v19, v20, 1.0
	v_fmac_f32_e32 v20, v21, v20
	v_div_scale_f32 v21, vcc, 2.0, v18, 2.0
	v_mul_f32_e32 v22, v21, v20
	v_fma_f32 v23, -v19, v22, v21
	v_fmac_f32_e32 v22, v23, v20
	v_fma_f32 v19, -v19, v22, v21
	v_div_fmas_f32 v19, v19, v20, v22
	v_div_fixup_f32 v18, v19, v18, 2.0
	v_sub_f32_e32 v18, 1.0, v18
	v_add_f32_e32 v18, 1.0, v18
	v_mul_f32_e32 v14, v14, v18
	v_mul_f32_e32 v18, 0x3d372713, v15
	v_mul_f32_e32 v18, v15, v18
	v_fma_f32 v18, v15, v18, v15
	v_mul_f32_e32 v18, 0x3f4c422a, v18
	v_add_f32_e32 v18, v18, v18
	v_mul_f32_e32 v18, 0x3fb8aa3b, v18
	v_exp_f32_e32 v18, v18
	v_mul_f32_e32 v15, 0.5, v15
	v_add_f32_e32 v18, 1.0, v18
	v_div_scale_f32 v19, s[28:29], v18, v18, 2.0
	v_rcp_f32_e32 v20, v19
	s_nop 0
	v_fma_f32 v21, -v19, v20, 1.0
	v_fmac_f32_e32 v20, v21, v20
	v_div_scale_f32 v21, vcc, 2.0, v18, 2.0
	v_mul_f32_e32 v22, v21, v20
	v_fma_f32 v23, -v19, v22, v21
	v_fmac_f32_e32 v22, v23, v20
	v_fma_f32 v19, -v19, v22, v21
	v_div_fmas_f32 v19, v19, v20, v22
	v_div_fixup_f32 v18, v19, v18, 2.0
	v_sub_f32_e32 v18, 1.0, v18
	v_add_f32_e32 v18, 1.0, v18
	v_mul_f32_e32 v15, v15, v18
	v_mul_f32_e32 v18, 0x3d372713, v16
	v_mul_f32_e32 v18, v16, v18
	v_fma_f32 v18, v16, v18, v16
	v_mul_f32_e32 v18, 0x3f4c422a, v18
	v_add_f32_e32 v18, v18, v18
	v_mul_f32_e32 v18, 0x3fb8aa3b, v18
	v_exp_f32_e32 v18, v18
	v_mul_f32_e32 v16, 0.5, v16
	v_add_f32_e32 v18, 1.0, v18
	v_div_scale_f32 v19, s[28:29], v18, v18, 2.0
	v_rcp_f32_e32 v20, v19
	s_nop 0
	v_fma_f32 v21, -v19, v20, 1.0
	v_fmac_f32_e32 v20, v21, v20
	v_div_scale_f32 v21, vcc, 2.0, v18, 2.0
	v_mul_f32_e32 v22, v21, v20
	v_fma_f32 v23, -v19, v22, v21
	v_fmac_f32_e32 v22, v23, v20
	v_fma_f32 v19, -v19, v22, v21
	v_div_fmas_f32 v19, v19, v20, v22
	v_div_fixup_f32 v18, v19, v18, 2.0
	v_sub_f32_e32 v18, 1.0, v18
	v_add_f32_e32 v18, 1.0, v18
	v_mul_f32_e32 v18, v16, v18
	v_mul_f32_e32 v16, 0x3d372713, v17
	v_mul_f32_e32 v16, v17, v16
	v_fma_f32 v16, v17, v16, v17
	v_mul_f32_e32 v16, 0x3f4c422a, v16
	v_add_f32_e32 v16, v16, v16
	v_mul_f32_e32 v16, 0x3fb8aa3b, v16
	v_exp_f32_e32 v16, v16
	v_mul_f32_e32 v17, 0.5, v17
	v_add_f32_e32 v16, 1.0, v16
	v_div_scale_f32 v19, s[28:29], v16, v16, 2.0
	v_rcp_f32_e32 v20, v19
	s_nop 0
	v_fma_f32 v21, -v19, v20, 1.0
	v_fmac_f32_e32 v20, v21, v20
	v_div_scale_f32 v21, vcc, 2.0, v16, 2.0
	v_mul_f32_e32 v22, v21, v20
	v_fma_f32 v23, -v19, v22, v21
	v_fmac_f32_e32 v22, v23, v20
	v_fma_f32 v19, -v19, v22, v21
	v_div_fmas_f32 v19, v19, v20, v22
	v_div_fixup_f32 v16, v19, v16, 2.0
	v_sub_f32_e32 v16, 1.0, v16
	v_add_f32_e32 v16, 1.0, v16
	v_mul_f32_e32 v17, v17, v16
	v_cvt_pk_bf16_f32 v192, v14, v15
	v_lshl_add_u64 v[14:15], s[26:27], 0, v[156:157]
	v_lshl_add_u64 v[14:15], v[14:15], 0, v[140:141]
	v_cvt_pk_bf16_f32 v193, v18, v17
	s_nop 0
	v_mov_b64_e32 v[16:17], v[180:181]
	v_mov_b64_e32 v[18:19], v[182:183]
	s_nop 0
	v_pk_add_f32 v[10:11], v[10:11], v[16:17]
	s_nop 0
	v_mul_f32_e32 v16, 0x3d372713, v10
	v_mul_f32_e32 v16, v10, v16
	v_fma_f32 v16, v10, v16, v10
	v_mul_f32_e32 v16, 0x3f4c422a, v16
	v_add_f32_e32 v16, v16, v16
	v_mul_f32_e32 v16, 0x3fb8aa3b, v16
	v_exp_f32_e32 v16, v16
	v_pk_add_f32 v[12:13], v[12:13], v[18:19]
	v_mul_f32_e32 v10, 0.5, v10
	v_add_f32_e32 v16, 1.0, v16
	v_div_scale_f32 v17, s[26:27], v16, v16, 2.0
	v_rcp_f32_e32 v18, v17
	s_nop 0
	v_fma_f32 v19, -v17, v18, 1.0
	v_fmac_f32_e32 v18, v19, v18
	v_div_scale_f32 v19, vcc, 2.0, v16, 2.0
	v_mul_f32_e32 v20, v19, v18
	v_fma_f32 v21, -v17, v20, v19
	v_fmac_f32_e32 v20, v21, v18
	v_fma_f32 v17, -v17, v20, v19
	v_div_fmas_f32 v17, v17, v18, v20
	v_div_fixup_f32 v16, v17, v16, 2.0
	v_sub_f32_e32 v16, 1.0, v16
	v_add_f32_e32 v16, 1.0, v16
	v_mul_f32_e32 v10, v10, v16
	v_mul_f32_e32 v16, 0x3d372713, v11
	v_mul_f32_e32 v16, v11, v16
	v_fma_f32 v16, v11, v16, v11
	v_mul_f32_e32 v16, 0x3f4c422a, v16
	v_add_f32_e32 v16, v16, v16
	v_mul_f32_e32 v16, 0x3fb8aa3b, v16
	v_exp_f32_e32 v16, v16
	v_mul_f32_e32 v11, 0.5, v11
	v_add_f32_e32 v16, 1.0, v16
	v_div_scale_f32 v17, s[26:27], v16, v16, 2.0
	v_rcp_f32_e32 v18, v17
	s_nop 0
	v_fma_f32 v19, -v17, v18, 1.0
	v_fmac_f32_e32 v18, v19, v18
	v_div_scale_f32 v19, vcc, 2.0, v16, 2.0
	v_mul_f32_e32 v20, v19, v18
	v_fma_f32 v21, -v17, v20, v19
	v_fmac_f32_e32 v20, v21, v18
	v_fma_f32 v17, -v17, v20, v19
	v_div_fmas_f32 v17, v17, v18, v20
	v_div_fixup_f32 v16, v17, v16, 2.0
	v_sub_f32_e32 v16, 1.0, v16
	v_add_f32_e32 v16, 1.0, v16
	v_mul_f32_e32 v11, v11, v16
	v_mul_f32_e32 v16, 0x3d372713, v12
	v_mul_f32_e32 v16, v12, v16
	v_fma_f32 v16, v12, v16, v12
	v_mul_f32_e32 v16, 0x3f4c422a, v16
	v_add_f32_e32 v16, v16, v16
	v_mul_f32_e32 v16, 0x3fb8aa3b, v16
	v_exp_f32_e32 v16, v16
	v_mul_f32_e32 v12, 0.5, v12
	v_cvt_pk_bf16_f32 v194, v10, v11
	v_add_f32_e32 v16, 1.0, v16
	v_div_scale_f32 v17, s[26:27], v16, v16, 2.0
	v_rcp_f32_e32 v18, v17
	s_nop 0
	v_fma_f32 v19, -v17, v18, 1.0
	v_fmac_f32_e32 v18, v19, v18
	v_div_scale_f32 v19, vcc, 2.0, v16, 2.0
	v_mul_f32_e32 v20, v19, v18
	v_fma_f32 v21, -v17, v20, v19
	v_fmac_f32_e32 v20, v21, v18
	v_fma_f32 v17, -v17, v20, v19
	v_div_fmas_f32 v17, v17, v18, v20
	v_div_fixup_f32 v16, v17, v16, 2.0
	v_sub_f32_e32 v16, 1.0, v16
	v_add_f32_e32 v16, 1.0, v16
	v_mul_f32_e32 v12, v12, v16
	v_mul_f32_e32 v16, 0x3d372713, v13
	v_mul_f32_e32 v16, v13, v16
	v_fma_f32 v16, v13, v16, v13
	v_mul_f32_e32 v16, 0x3f4c422a, v16
	v_add_f32_e32 v16, v16, v16
	v_mul_f32_e32 v16, 0x3fb8aa3b, v16
	v_exp_f32_e32 v16, v16
	v_mul_f32_e32 v13, 0.5, v13
	v_add_f32_e32 v16, 1.0, v16
	v_div_scale_f32 v17, s[26:27], v16, v16, 2.0
	v_rcp_f32_e32 v18, v17
	s_nop 0
	v_fma_f32 v19, -v17, v18, 1.0
	v_fmac_f32_e32 v18, v19, v18
	v_div_scale_f32 v19, vcc, 2.0, v16, 2.0
	v_mul_f32_e32 v20, v19, v18
	v_fma_f32 v21, -v17, v20, v19
	v_fmac_f32_e32 v20, v21, v18
	v_fma_f32 v17, -v17, v20, v19
	v_div_fmas_f32 v17, v17, v18, v20
	v_div_fixup_f32 v16, v17, v16, 2.0
	v_sub_f32_e32 v16, 1.0, v16
	v_add_f32_e32 v16, 1.0, v16
	v_mul_f32_e32 v13, v13, v16
	v_cvt_pk_bf16_f32 v195, v12, v13
	s_nop 1
	v_permlane16_swap_b32_e32 v192, v194
	v_permlane16_swap_b32_e32 v193, v195
	v_lshl_add_u64 v[200:201], v[14:15], 0, v[202:203]
	global_store_dwordx4 v[200:201], v[192:195], off
	v_mov_b64_e32 v[10:11], v[184:185]
	v_mov_b64_e32 v[12:13], v[186:187]
	s_nop 0
	v_pk_add_f32 v[6:7], v[6:7], v[10:11]
	s_nop 0
	v_mul_f32_e32 v10, 0x3d372713, v6
	v_mul_f32_e32 v10, v6, v10
	v_fma_f32 v10, v6, v10, v6
	v_mul_f32_e32 v10, 0x3f4c422a, v10
	v_add_f32_e32 v10, v10, v10
	v_mul_f32_e32 v10, 0x3fb8aa3b, v10
	v_exp_f32_e32 v10, v10
	v_pk_add_f32 v[8:9], v[8:9], v[12:13]
	v_mul_f32_e32 v6, 0.5, v6
	v_add_f32_e32 v10, 1.0, v10
	v_div_scale_f32 v11, s[26:27], v10, v10, 2.0
	v_rcp_f32_e32 v12, v11
	s_nop 0
	v_fma_f32 v13, -v11, v12, 1.0
	v_fmac_f32_e32 v12, v13, v12
	v_div_scale_f32 v13, vcc, 2.0, v10, 2.0
	v_mul_f32_e32 v16, v13, v12
	v_fma_f32 v17, -v11, v16, v13
	v_fmac_f32_e32 v16, v17, v12
	v_fma_f32 v11, -v11, v16, v13
	v_div_fmas_f32 v11, v11, v12, v16
	v_div_fixup_f32 v10, v11, v10, 2.0
	v_sub_f32_e32 v10, 1.0, v10
	v_add_f32_e32 v10, 1.0, v10
	v_mul_f32_e32 v6, v6, v10
	v_mul_f32_e32 v10, 0x3d372713, v7
	v_mul_f32_e32 v10, v7, v10
	v_fma_f32 v10, v7, v10, v7
	v_mul_f32_e32 v10, 0x3f4c422a, v10
	v_add_f32_e32 v10, v10, v10
	v_mul_f32_e32 v10, 0x3fb8aa3b, v10
	v_exp_f32_e32 v10, v10
	v_mul_f32_e32 v7, 0.5, v7
	v_add_f32_e32 v10, 1.0, v10
	v_div_scale_f32 v11, s[26:27], v10, v10, 2.0
	v_rcp_f32_e32 v12, v11
	s_nop 0
	v_fma_f32 v13, -v11, v12, 1.0
	v_fmac_f32_e32 v12, v13, v12
	v_div_scale_f32 v13, vcc, 2.0, v10, 2.0
	v_mul_f32_e32 v16, v13, v12
	v_fma_f32 v17, -v11, v16, v13
	v_fmac_f32_e32 v16, v17, v12
	v_fma_f32 v11, -v11, v16, v13
	v_div_fmas_f32 v11, v11, v12, v16
	v_div_fixup_f32 v10, v11, v10, 2.0
	v_sub_f32_e32 v10, 1.0, v10
	v_add_f32_e32 v10, 1.0, v10
	v_mul_f32_e32 v7, v7, v10
	v_mul_f32_e32 v10, 0x3d372713, v8
	v_mul_f32_e32 v10, v8, v10
	v_fma_f32 v10, v8, v10, v8
	v_mul_f32_e32 v10, 0x3f4c422a, v10
	v_add_f32_e32 v10, v10, v10
	v_mul_f32_e32 v10, 0x3fb8aa3b, v10
	v_exp_f32_e32 v10, v10
	v_mul_f32_e32 v8, 0.5, v8
	v_cvt_pk_bf16_f32 v196, v6, v7
	v_add_f32_e32 v10, 1.0, v10
	v_div_scale_f32 v11, s[26:27], v10, v10, 2.0
	v_rcp_f32_e32 v12, v11
	s_nop 0
	v_fma_f32 v13, -v11, v12, 1.0
	v_fmac_f32_e32 v12, v13, v12
	v_div_scale_f32 v13, vcc, 2.0, v10, 2.0
	v_mul_f32_e32 v16, v13, v12
	v_fma_f32 v17, -v11, v16, v13
	v_fmac_f32_e32 v16, v17, v12
	v_fma_f32 v11, -v11, v16, v13
	v_div_fmas_f32 v11, v11, v12, v16
	v_div_fixup_f32 v10, v11, v10, 2.0
	v_sub_f32_e32 v10, 1.0, v10
	v_add_f32_e32 v10, 1.0, v10
	v_mul_f32_e32 v8, v8, v10
	v_mul_f32_e32 v10, 0x3d372713, v9
	v_mul_f32_e32 v10, v9, v10
	v_fma_f32 v10, v9, v10, v9
	v_mul_f32_e32 v10, 0x3f4c422a, v10
	v_add_f32_e32 v10, v10, v10
	v_mul_f32_e32 v10, 0x3fb8aa3b, v10
	v_exp_f32_e32 v10, v10
	v_mul_f32_e32 v9, 0.5, v9
	v_add_f32_e32 v10, 1.0, v10
	v_div_scale_f32 v11, s[26:27], v10, v10, 2.0
	v_rcp_f32_e32 v12, v11
	s_nop 0
	v_fma_f32 v13, -v11, v12, 1.0
	v_fmac_f32_e32 v12, v13, v12
	v_div_scale_f32 v13, vcc, 2.0, v10, 2.0
	v_mul_f32_e32 v16, v13, v12
	v_fma_f32 v17, -v11, v16, v13
	v_fmac_f32_e32 v16, v17, v12
	v_fma_f32 v11, -v11, v16, v13
	v_div_fmas_f32 v11, v11, v12, v16
	v_div_fixup_f32 v10, v11, v10, 2.0
	v_sub_f32_e32 v10, 1.0, v10
	v_add_f32_e32 v10, 1.0, v10
	v_mul_f32_e32 v9, v9, v10
	v_cvt_pk_bf16_f32 v197, v8, v9
	s_nop 0
	v_mov_b64_e32 v[6:7], v[188:189]
	v_mov_b64_e32 v[8:9], v[190:191]
	s_nop 0
	v_pk_add_f32 v[2:3], v[2:3], v[6:7]
	s_nop 0
	v_mul_f32_e32 v6, 0x3d372713, v2
	v_mul_f32_e32 v6, v2, v6
	v_fma_f32 v6, v2, v6, v2
	v_mul_f32_e32 v6, 0x3f4c422a, v6
	v_add_f32_e32 v6, v6, v6
	v_mul_f32_e32 v6, 0x3fb8aa3b, v6
	v_exp_f32_e32 v6, v6
	v_pk_add_f32 v[4:5], v[4:5], v[8:9]
	v_mul_f32_e32 v2, 0.5, v2
	v_add_f32_e32 v6, 1.0, v6
	v_div_scale_f32 v7, s[26:27], v6, v6, 2.0
	v_rcp_f32_e32 v8, v7
	s_nop 0
	v_fma_f32 v9, -v7, v8, 1.0
	v_fmac_f32_e32 v8, v9, v8
	v_div_scale_f32 v9, vcc, 2.0, v6, 2.0
	v_mul_f32_e32 v10, v9, v8
	v_fma_f32 v11, -v7, v10, v9
	v_fmac_f32_e32 v10, v11, v8
	v_fma_f32 v7, -v7, v10, v9
	v_div_fmas_f32 v7, v7, v8, v10
	v_div_fixup_f32 v6, v7, v6, 2.0
	v_sub_f32_e32 v6, 1.0, v6
	v_add_f32_e32 v6, 1.0, v6
	v_mul_f32_e32 v2, v2, v6
	v_mul_f32_e32 v6, 0x3d372713, v3
	v_mul_f32_e32 v6, v3, v6
	v_fma_f32 v6, v3, v6, v3
	v_mul_f32_e32 v6, 0x3f4c422a, v6
	v_add_f32_e32 v6, v6, v6
	v_mul_f32_e32 v6, 0x3fb8aa3b, v6
	v_exp_f32_e32 v6, v6
	v_mul_f32_e32 v3, 0.5, v3
	v_add_f32_e32 v6, 1.0, v6
	v_div_scale_f32 v7, s[26:27], v6, v6, 2.0
	v_rcp_f32_e32 v8, v7
	s_nop 0
	v_fma_f32 v9, -v7, v8, 1.0
	v_fmac_f32_e32 v8, v9, v8
	v_div_scale_f32 v9, vcc, 2.0, v6, 2.0
	v_mul_f32_e32 v10, v9, v8
	v_fma_f32 v11, -v7, v10, v9
	v_fmac_f32_e32 v10, v11, v8
	v_fma_f32 v7, -v7, v10, v9
	v_div_fmas_f32 v7, v7, v8, v10
	v_div_fixup_f32 v6, v7, v6, 2.0
	v_sub_f32_e32 v6, 1.0, v6
	v_add_f32_e32 v6, 1.0, v6
	v_mul_f32_e32 v3, v3, v6
	v_mul_f32_e32 v6, 0x3d372713, v4
	v_mul_f32_e32 v6, v4, v6
	v_fma_f32 v6, v4, v6, v4
	v_mul_f32_e32 v6, 0x3f4c422a, v6
	v_add_f32_e32 v6, v6, v6
	v_mul_f32_e32 v6, 0x3fb8aa3b, v6
	v_exp_f32_e32 v6, v6
	v_mul_f32_e32 v4, 0.5, v4
	v_cvt_pk_bf16_f32 v198, v2, v3
	v_add_f32_e32 v6, 1.0, v6
	v_div_scale_f32 v7, s[26:27], v6, v6, 2.0
	v_rcp_f32_e32 v8, v7
	s_nop 0
	v_fma_f32 v9, -v7, v8, 1.0
	v_fmac_f32_e32 v8, v9, v8
	v_div_scale_f32 v9, vcc, 2.0, v6, 2.0
	v_mul_f32_e32 v10, v9, v8
	v_fma_f32 v11, -v7, v10, v9
	v_fmac_f32_e32 v10, v11, v8
	v_fma_f32 v7, -v7, v10, v9
	v_div_fmas_f32 v7, v7, v8, v10
	v_div_fixup_f32 v6, v7, v6, 2.0
	v_sub_f32_e32 v6, 1.0, v6
	v_add_f32_e32 v6, 1.0, v6
	v_mul_f32_e32 v4, v4, v6
	v_mul_f32_e32 v6, 0x3d372713, v5
	v_mul_f32_e32 v6, v5, v6
	v_fma_f32 v6, v5, v6, v5
	v_mul_f32_e32 v6, 0x3f4c422a, v6
	v_add_f32_e32 v6, v6, v6
	v_mul_f32_e32 v6, 0x3fb8aa3b, v6
	v_exp_f32_e32 v6, v6
	v_mul_f32_e32 v5, 0.5, v5
	v_add_f32_e32 v6, 1.0, v6
	v_div_scale_f32 v7, s[26:27], v6, v6, 2.0
	v_rcp_f32_e32 v8, v7
	s_mov_b64 s[26:27], -1
	v_fma_f32 v9, -v7, v8, 1.0
	v_fmac_f32_e32 v8, v9, v8
	v_div_scale_f32 v9, vcc, 2.0, v6, 2.0
	v_mul_f32_e32 v10, v9, v8
	v_fma_f32 v11, -v7, v10, v9
	v_fmac_f32_e32 v10, v11, v8
	v_fma_f32 v7, -v7, v10, v9
	v_div_fmas_f32 v7, v7, v8, v10
	v_div_fixup_f32 v6, v7, v6, 2.0
	v_sub_f32_e32 v6, 1.0, v6
	v_add_f32_e32 v6, 1.0, v6
	s_and_b64 vcc, exec, s[4:5]
	v_mul_f32_e32 v5, v5, v6
	v_cvt_pk_bf16_f32 v199, v4, v5
	s_nop 1
	v_permlane16_swap_b32_e32 v196, v198
	v_permlane16_swap_b32_e32 v197, v199
	v_lshl_add_u64 v[200:201], v[14:15], 0, v[202:203]
	global_store_dwordx4 v[200:201], v[196:199], off offset:256
	s_cbranch_vccnz .LBB0_664
	s_andn2_b64 vcc, exec, s[14:15]
	s_cbranch_vccnz .LBB0_663
	s_barrier
	s_branch .LBB0_663
